# one s_waitcnt per MFMA pair (instead of per MFMA) in the MLA and NA fast slots
# speedup vs baseline: 1.1255x; 1.0010x over previous
.Lna_wloop:
	s_sub_i32 s36, s24, s23
	s_cmp_lt_u32 s36, 8
	s_cselect_b64 s[40:41], -1, 0
	s_add_i32 s36, s36, 1
	s_cmp_lt_u32 s36, 8
	s_cselect_b64 s[42:43], -1, 0
	s_and_b64 s[44:45], s[40:41], s[42:43]
	s_cmp_eq_u64 s[44:45], 0
	s_cbranch_scc1 .Lna_slow_w1
	ds_read_b128 v[146:149], v199 offset:0
	ds_read_b128 v[150:153], v200 offset:0
	ds_read_b128 v[154:157], v199 offset:32
	ds_read_b128 v[158:161], v200 offset:32
	v_add_u32_e32 v210, s25, v208
	v_add_u32_e32 v211, s25, v209
	v_exp_f32_e32 v66, v66
	v_exp_f32_e32 v67, v67
	v_exp_f32_e32 v68, v68
	v_exp_f32_e32 v69, v69
	s_waitcnt lgkmcnt(2)
	v_mfma_f32_32x32x16_bf16 v[34:49], v[146:149], v[98:101], v[114:129]
	ds_read_b128 v[146:149], v199 offset:64
	v_add_f32_e32 v213, v213, v66
	v_add_f32_e32 v214, v214, v67
	v_add_f32_e32 v213, v213, v68
	v_add_f32_e32 v214, v214, v69
	v_exp_f32_e32 v70, v70
	v_exp_f32_e32 v71, v71
	v_mfma_f32_32x32x16_bf16 v[50:65], v[150:153], v[98:101], v[130:145]
	ds_read_b128 v[150:153], v200 offset:64
	v_exp_f32_e32 v72, v72
	v_exp_f32_e32 v73, v73
	v_add_f32_e32 v213, v213, v70
	v_add_f32_e32 v214, v214, v71
	s_waitcnt lgkmcnt(2)
	v_mfma_f32_32x32x16_bf16 v[34:49], v[154:157], v[102:105], v[34:49]
	ds_read_b128 v[154:157], v199 offset:96
	v_add_f32_e32 v213, v213, v72
	v_add_f32_e32 v214, v214, v73
	v_cvt_pk_bf16_f32 v66, v66, v67
	v_cvt_pk_bf16_f32 v67, v68, v69
	v_cvt_pk_bf16_f32 v68, v70, v71
	v_cvt_pk_bf16_f32 v69, v72, v73
	v_exp_f32_e32 v74, v74
	v_mfma_f32_32x32x16_bf16 v[50:65], v[158:161], v[102:105], v[50:65]
	ds_read_b128 v[158:161], v200 offset:96
	v_exp_f32_e32 v75, v75
	v_exp_f32_e32 v76, v76
	v_exp_f32_e32 v77, v77
	s_waitcnt lgkmcnt(2)
	v_mfma_f32_32x32x16_bf16 v[34:49], v[146:149], v[106:109], v[34:49]
	ds_read_b64 v[162:163], v201 offset:8704
	ds_read_b64 v[164:165], v201 offset:8720
	v_add_f32_e32 v213, v213, v74
	v_add_f32_e32 v214, v214, v75
	v_add_f32_e32 v213, v213, v76
	v_add_f32_e32 v214, v214, v77
	v_exp_f32_e32 v78, v78
	v_exp_f32_e32 v79, v79
	v_mfma_f32_32x32x16_bf16 v[50:65], v[150:153], v[106:109], v[50:65]
	ds_read_b64 v[166:167], v201 offset:13056
	ds_read_b64 v[168:169], v201 offset:13072
	v_exp_f32_e32 v80, v80
	v_exp_f32_e32 v81, v81
	v_add_f32_e32 v213, v213, v78
	v_add_f32_e32 v214, v214, v79
	s_waitcnt lgkmcnt(4)
	v_mfma_f32_32x32x16_bf16 v[34:49], v[154:157], v[110:113], v[34:49]
	ds_read_b64 v[170:171], v201 offset:8736
	ds_read_b64 v[172:173], v201 offset:8752
	v_add_f32_e32 v213, v213, v80
	v_add_f32_e32 v214, v214, v81
	v_cvt_pk_bf16_f32 v74, v74, v75
	v_cvt_pk_bf16_f32 v75, v76, v77
	v_cvt_pk_bf16_f32 v76, v78, v79
	v_cvt_pk_bf16_f32 v77, v80, v81
	v_exp_f32_e32 v82, v82
	v_mfma_f32_32x32x16_bf16 v[50:65], v[158:161], v[110:113], v[50:65]
	ds_read_b64 v[174:175], v201 offset:13088
	ds_read_b64 v[176:177], v201 offset:13104
	ds_read_b128 v[146:149], v210 offset:0
	ds_read_b128 v[150:153], v210 offset:32
	ds_read_b128 v[154:157], v210 offset:64
	ds_read_b128 v[158:161], v210 offset:96
	ds_read_b128 v[180:183], v211
	v_exp_f32_e32 v83, v83
	v_exp_f32_e32 v84, v84
	v_exp_f32_e32 v85, v85
	s_waitcnt lgkmcnt(11)
	v_mfma_f32_32x32x16_bf16 v[2:17], v[162:165], v[66:69], v[2:17]
	ds_read_b64 v[162:163], v202 offset:8704
	ds_read_b64 v[164:165], v203 offset:8704
	v_add_f32_e32 v213, v213, v82
	v_add_f32_e32 v214, v214, v83
	v_add_f32_e32 v213, v213, v84
	v_add_f32_e32 v214, v214, v85
	v_cvt_pk_bf16_f32 v184, v82, v83
	v_cvt_pk_bf16_f32 v185, v84, v85
	s_waitcnt lgkmcnt(11)
	v_mfma_f32_32x32x16_bf16 v[18:33], v[166:169], v[66:69], v[18:33]
	ds_read_b64 v[166:167], v202 offset:13056
	ds_read_b64 v[168:169], v203 offset:13056
	s_waitcnt lgkmcnt(4)
	v_add_f32_e32 v34, v34, v146
	v_add_f32_e32 v35, v35, v147
	v_add_f32_e32 v36, v36, v148
	v_add_f32_e32 v37, v37, v149
	v_add_f32_e32 v38, v38, v150
	v_add_f32_e32 v39, v39, v151
	v_add_f32_e32 v40, v40, v152
	v_add_f32_e32 v41, v41, v153
	v_mfma_f32_32x32x16_bf16 v[2:17], v[170:173], v[74:77], v[2:17]
	v_add_f32_e32 v42, v42, v154
	v_add_f32_e32 v43, v43, v155
	v_add_f32_e32 v44, v44, v156
	v_add_f32_e32 v45, v45, v157
	v_add_f32_e32 v46, v46, v158
	v_add_f32_e32 v47, v47, v159
	v_add_f32_e32 v48, v48, v160
	v_mfma_f32_32x32x16_bf16 v[18:33], v[174:177], v[74:77], v[18:33]
	s_waitcnt vmcnt(2)
	ds_write_b128 v204, v[230:233] offset:9216
	ds_write_b64 v205, v[234:235] offset:0
	ds_write_b64 v205, v[236:237] offset:8
	global_load_dwordx4 v[230:233], v206, s[12:13]
	s_add_i32 s20, s20, 1
	s_add_u32 s12, s12, 0x2000
	s_addc_u32 s13, s13, 0
	s_cmp_eq_u32 s20, s22
	s_cselect_b32 s12, s16, s12
	s_cselect_b32 s13, s17, s13
	global_load_dwordx4 v[234:237], v207, s[14:15]
	s_add_i32 s21, s21, 1
	s_add_u32 s14, s14, 0x80
	s_addc_u32 s15, s15, 0
	s_cmp_eq_u32 s21, s22
	s_cselect_b32 s14, s18, s14
	s_cselect_b32 s15, s19, s15
	v_add_f32_e32 v49, v49, v161
	v_add_f32_e32 v50, v50, v180
	v_add_f32_e32 v51, v51, v181
	v_add_f32_e32 v52, v52, v182
	v_add_f32_e32 v53, v53, v183
	v_max3_f32 v216, v34, v35, v36
	v_max3_f32 v217, v44, v45, v46
	s_waitcnt lgkmcnt(5)
	v_mfma_f32_32x32x16_bf16 v[2:17], v[162:165], v[184:187], v[2:17]
	v_max3_f32 v216, v216, v37, v38
	v_max3_f32 v217, v217, v47, v48
	v_max3_f32 v216, v216, v39, v40
	v_max3_f32 v217, v217, v49, v50
	v_max3_f32 v216, v216, v41, v42
	v_max3_f32 v217, v217, v51, v52
	v_max_f32_e32 v216, v216, v43
	s_waitcnt lgkmcnt(3)
	v_mfma_f32_32x32x16_bf16 v[18:33], v[166:169], v[184:187], v[18:33]
	v_max_f32_e32 v217, v217, v53
	v_max_f32_e32 v216, v216, v217
	v_mov_b32_e32 v217, v216
	s_nop 1
	v_permlane32_swap_b32_e32 v216, v217
	v_max_f32_e32 v215, v216, v217
	v_cmp_lt_f32_e32 vcc, 4.0, v215
	s_or_b64 s[28:29], vcc, s[26:27]
	s_cmp_lg_u64 s[28:29], 0
	s_cbranch_scc0 .Lna_nr_w1f
	s_nop 15
	v_max_f32_e32 v216, v215, v220
	v_exp_f32_e64 v217, -v216
	v_add_f32_e32 v212, v212, v216
	v_and_b32_e32 v217, v217, v221
	v_sub_f32_e32 v34, v34, v216
	v_sub_f32_e32 v35, v35, v216
	v_sub_f32_e32 v36, v36, v216
	v_sub_f32_e32 v37, v37, v216
	v_sub_f32_e32 v38, v38, v216
	v_sub_f32_e32 v39, v39, v216
	v_sub_f32_e32 v40, v40, v216
	v_sub_f32_e32 v41, v41, v216
	v_sub_f32_e32 v42, v42, v216
	v_sub_f32_e32 v43, v43, v216
	v_sub_f32_e32 v44, v44, v216
	v_sub_f32_e32 v45, v45, v216
	v_sub_f32_e32 v46, v46, v216
	v_sub_f32_e32 v47, v47, v216
	v_sub_f32_e32 v48, v48, v216
	v_sub_f32_e32 v49, v49, v216
	v_sub_f32_e32 v50, v50, v216
	v_sub_f32_e32 v51, v51, v216
	v_sub_f32_e32 v52, v52, v216
	v_sub_f32_e32 v53, v53, v216
	v_sub_f32_e32 v114, v114, v216
	v_sub_f32_e32 v115, v115, v216
	v_sub_f32_e32 v116, v116, v216
	v_sub_f32_e32 v117, v117, v216
	v_sub_f32_e32 v118, v118, v216
	v_sub_f32_e32 v119, v119, v216
	v_sub_f32_e32 v120, v120, v216
	v_sub_f32_e32 v121, v121, v216
	v_sub_f32_e32 v122, v122, v216
	v_sub_f32_e32 v123, v123, v216
	v_sub_f32_e32 v124, v124, v216
	v_sub_f32_e32 v125, v125, v216
	v_sub_f32_e32 v126, v126, v216
	v_sub_f32_e32 v127, v127, v216
	v_sub_f32_e32 v128, v128, v216
	v_sub_f32_e32 v129, v129, v216
	v_sub_f32_e32 v130, v130, v216
	v_sub_f32_e32 v131, v131, v216
	v_sub_f32_e32 v132, v132, v216
	v_sub_f32_e32 v133, v133, v216
	v_mul_f32_e32 v213, v213, v217
	v_mul_f32_e32 v214, v214, v217
	v_mul_f32_e32 v2, v2, v217
	v_mul_f32_e32 v3, v3, v217
	v_mul_f32_e32 v4, v4, v217
	v_mul_f32_e32 v5, v5, v217
	v_mul_f32_e32 v6, v6, v217
	v_mul_f32_e32 v7, v7, v217
	v_mul_f32_e32 v8, v8, v217
	v_mul_f32_e32 v9, v9, v217
	v_mul_f32_e32 v10, v10, v217
	v_mul_f32_e32 v11, v11, v217
	v_mul_f32_e32 v12, v12, v217
	v_mul_f32_e32 v13, v13, v217
	v_mul_f32_e32 v14, v14, v217
	v_mul_f32_e32 v15, v15, v217
	v_mul_f32_e32 v16, v16, v217
	v_mul_f32_e32 v17, v17, v217
	v_mul_f32_e32 v18, v18, v217
	v_mul_f32_e32 v19, v19, v217
	v_mul_f32_e32 v20, v20, v217
	v_mul_f32_e32 v21, v21, v217
	v_mul_f32_e32 v22, v22, v217
	v_mul_f32_e32 v23, v23, v217
	v_mul_f32_e32 v24, v24, v217
	v_mul_f32_e32 v25, v25, v217
	v_mul_f32_e32 v26, v26, v217
	v_mul_f32_e32 v27, v27, v217
	v_mul_f32_e32 v28, v28, v217
	v_mul_f32_e32 v29, v29, v217
	v_mul_f32_e32 v30, v30, v217
	v_mul_f32_e32 v31, v31, v217
	v_mul_f32_e32 v32, v32, v217
	v_mul_f32_e32 v33, v33, v217
	v_mov_b32_e32 v220, 0
	v_mov_b32_e32 v221, -1
	s_mov_b64 s[26:27], 0

.Lna_done_w1:
	s_add_i32 s24, s24, 1
	s_add_i32 s25, s25, 0x150
	s_sub_i32 s36, s24, s23
	s_cmp_lt_u32 s36, 8
	s_cselect_b64 s[40:41], -1, 0
	s_add_i32 s36, s36, 1
	s_cmp_lt_u32 s36, 8
	s_cselect_b64 s[42:43], -1, 0
	s_and_b64 s[44:45], s[40:41], s[42:43]
	s_cmp_eq_u64 s[44:45], 0
	s_cbranch_scc1 .Lna_slow_w0
	ds_read_b128 v[146:149], v199 offset:9216
	ds_read_b128 v[150:153], v200 offset:9216
	ds_read_b128 v[154:157], v199 offset:9248
	ds_read_b128 v[158:161], v200 offset:9248
	v_add_u32_e32 v210, s25, v208
	v_add_u32_e32 v211, s25, v209
	v_exp_f32_e32 v34, v34
	v_exp_f32_e32 v35, v35
	v_exp_f32_e32 v36, v36
	v_exp_f32_e32 v37, v37
	s_waitcnt lgkmcnt(2)
	v_mfma_f32_32x32x16_bf16 v[66:81], v[146:149], v[98:101], v[114:129]
	ds_read_b128 v[146:149], v199 offset:9280
	v_add_f32_e32 v213, v213, v34
	v_add_f32_e32 v214, v214, v35
	v_add_f32_e32 v213, v213, v36
	v_add_f32_e32 v214, v214, v37
	v_exp_f32_e32 v38, v38
	v_exp_f32_e32 v39, v39
	v_mfma_f32_32x32x16_bf16 v[82:97], v[150:153], v[98:101], v[130:145]
	ds_read_b128 v[150:153], v200 offset:9280
	v_exp_f32_e32 v40, v40
	v_exp_f32_e32 v41, v41
	v_add_f32_e32 v213, v213, v38
	v_add_f32_e32 v214, v214, v39
	s_waitcnt lgkmcnt(2)
	v_mfma_f32_32x32x16_bf16 v[66:81], v[154:157], v[102:105], v[66:81]
	ds_read_b128 v[154:157], v199 offset:9312
	v_add_f32_e32 v213, v213, v40
	v_add_f32_e32 v214, v214, v41
	v_cvt_pk_bf16_f32 v34, v34, v35
	v_cvt_pk_bf16_f32 v35, v36, v37
	v_cvt_pk_bf16_f32 v36, v38, v39
	v_cvt_pk_bf16_f32 v37, v40, v41
	v_exp_f32_e32 v42, v42
	v_mfma_f32_32x32x16_bf16 v[82:97], v[158:161], v[102:105], v[82:97]
	ds_read_b128 v[158:161], v200 offset:9312
	v_exp_f32_e32 v43, v43
	v_exp_f32_e32 v44, v44
	v_exp_f32_e32 v45, v45
	s_waitcnt lgkmcnt(2)
	v_mfma_f32_32x32x16_bf16 v[66:81], v[146:149], v[106:109], v[66:81]
	ds_read_b64 v[162:163], v201 offset:0
	ds_read_b64 v[164:165], v201 offset:16
	v_add_f32_e32 v213, v213, v42
	v_add_f32_e32 v214, v214, v43
	v_add_f32_e32 v213, v213, v44
	v_add_f32_e32 v214, v214, v45
	v_exp_f32_e32 v46, v46
	v_exp_f32_e32 v47, v47
	v_mfma_f32_32x32x16_bf16 v[82:97], v[150:153], v[106:109], v[82:97]
	ds_read_b64 v[166:167], v201 offset:4352
	ds_read_b64 v[168:169], v201 offset:4368
	v_exp_f32_e32 v48, v48
	v_exp_f32_e32 v49, v49
	v_add_f32_e32 v213, v213, v46
	v_add_f32_e32 v214, v214, v47
	s_waitcnt lgkmcnt(4)
	v_mfma_f32_32x32x16_bf16 v[66:81], v[154:157], v[110:113], v[66:81]
	ds_read_b64 v[170:171], v201 offset:32
	ds_read_b64 v[172:173], v201 offset:48
	v_add_f32_e32 v213, v213, v48
	v_add_f32_e32 v214, v214, v49
	v_cvt_pk_bf16_f32 v42, v42, v43
	v_cvt_pk_bf16_f32 v43, v44, v45
	v_cvt_pk_bf16_f32 v44, v46, v47
	v_cvt_pk_bf16_f32 v45, v48, v49
	v_exp_f32_e32 v50, v50
	v_mfma_f32_32x32x16_bf16 v[82:97], v[158:161], v[110:113], v[82:97]
	ds_read_b64 v[174:175], v201 offset:4384
	ds_read_b64 v[176:177], v201 offset:4400
	ds_read_b128 v[146:149], v210 offset:0
	ds_read_b128 v[150:153], v210 offset:32
	ds_read_b128 v[154:157], v210 offset:64
	ds_read_b128 v[158:161], v210 offset:96
	ds_read_b128 v[180:183], v211
	v_exp_f32_e32 v51, v51
	v_exp_f32_e32 v52, v52
	v_exp_f32_e32 v53, v53
	s_waitcnt lgkmcnt(11)
	v_mfma_f32_32x32x16_bf16 v[2:17], v[162:165], v[34:37], v[2:17]
	ds_read_b64 v[162:163], v202 offset:0
	ds_read_b64 v[164:165], v203 offset:0
	v_add_f32_e32 v213, v213, v50
	v_add_f32_e32 v214, v214, v51
	v_add_f32_e32 v213, v213, v52
	v_add_f32_e32 v214, v214, v53
	v_cvt_pk_bf16_f32 v184, v50, v51
	v_cvt_pk_bf16_f32 v185, v52, v53
	s_waitcnt lgkmcnt(11)
	v_mfma_f32_32x32x16_bf16 v[18:33], v[166:169], v[34:37], v[18:33]
	ds_read_b64 v[166:167], v202 offset:4352
	ds_read_b64 v[168:169], v203 offset:4352
	s_waitcnt lgkmcnt(4)
	v_add_f32_e32 v66, v66, v146
	v_add_f32_e32 v67, v67, v147
	v_add_f32_e32 v68, v68, v148
	v_add_f32_e32 v69, v69, v149
	v_add_f32_e32 v70, v70, v150
	v_add_f32_e32 v71, v71, v151
	v_add_f32_e32 v72, v72, v152
	v_add_f32_e32 v73, v73, v153
	v_mfma_f32_32x32x16_bf16 v[2:17], v[170:173], v[42:45], v[2:17]
	v_add_f32_e32 v74, v74, v154
	v_add_f32_e32 v75, v75, v155
	v_add_f32_e32 v76, v76, v156
	v_add_f32_e32 v77, v77, v157
	v_add_f32_e32 v78, v78, v158
	v_add_f32_e32 v79, v79, v159
	v_add_f32_e32 v80, v80, v160
	v_mfma_f32_32x32x16_bf16 v[18:33], v[174:177], v[42:45], v[18:33]
	s_waitcnt vmcnt(2)
	ds_write_b128 v204, v[188:191] offset:0
	ds_write_b64 v205, v[192:193] offset:8704
	ds_write_b64 v205, v[194:195] offset:8712
	global_load_dwordx4 v[188:191], v206, s[12:13]
	s_add_i32 s20, s20, 1
	s_add_u32 s12, s12, 0x2000
	s_addc_u32 s13, s13, 0
	s_cmp_eq_u32 s20, s22
	s_cselect_b32 s12, s16, s12
	s_cselect_b32 s13, s17, s13
	global_load_dwordx4 v[192:195], v207, s[14:15]
	s_add_i32 s21, s21, 1
	s_add_u32 s14, s14, 0x80
	s_addc_u32 s15, s15, 0
	s_cmp_eq_u32 s21, s22
	s_cselect_b32 s14, s18, s14
	s_cselect_b32 s15, s19, s15
	v_add_f32_e32 v81, v81, v161
	v_add_f32_e32 v82, v82, v180
	v_add_f32_e32 v83, v83, v181
	v_add_f32_e32 v84, v84, v182
	v_add_f32_e32 v85, v85, v183
	v_max3_f32 v216, v66, v67, v68
	v_max3_f32 v217, v76, v77, v78
	s_waitcnt lgkmcnt(5)
	v_mfma_f32_32x32x16_bf16 v[2:17], v[162:165], v[184:187], v[2:17]
	v_max3_f32 v216, v216, v69, v70
	v_max3_f32 v217, v217, v79, v80
	v_max3_f32 v216, v216, v71, v72
	v_max3_f32 v217, v217, v81, v82
	v_max3_f32 v216, v216, v73, v74
	v_max3_f32 v217, v217, v83, v84
	v_max_f32_e32 v216, v216, v75
	s_waitcnt lgkmcnt(3)
	v_mfma_f32_32x32x16_bf16 v[18:33], v[166:169], v[184:187], v[18:33]
	v_max_f32_e32 v217, v217, v85
	v_max_f32_e32 v216, v216, v217
	v_mov_b32_e32 v217, v216
	s_nop 1
	v_permlane32_swap_b32_e32 v216, v217
	v_max_f32_e32 v215, v216, v217
	v_cmp_lt_f32_e32 vcc, 4.0, v215
	s_or_b64 s[28:29], vcc, s[26:27]
	s_cmp_lg_u64 s[28:29], 0
	s_cbranch_scc0 .Lna_nr_w0f
	s_nop 15
	v_max_f32_e32 v216, v215, v220
	v_exp_f32_e64 v217, -v216
	v_add_f32_e32 v212, v212, v216
	v_and_b32_e32 v217, v217, v221
	v_sub_f32_e32 v66, v66, v216
	v_sub_f32_e32 v67, v67, v216
	v_sub_f32_e32 v68, v68, v216
	v_sub_f32_e32 v69, v69, v216
	v_sub_f32_e32 v70, v70, v216
	v_sub_f32_e32 v71, v71, v216
	v_sub_f32_e32 v72, v72, v216
	v_sub_f32_e32 v73, v73, v216
	v_sub_f32_e32 v74, v74, v216
	v_sub_f32_e32 v75, v75, v216
	v_sub_f32_e32 v76, v76, v216
	v_sub_f32_e32 v77, v77, v216
	v_sub_f32_e32 v78, v78, v216
	v_sub_f32_e32 v79, v79, v216
	v_sub_f32_e32 v80, v80, v216
	v_sub_f32_e32 v81, v81, v216
	v_sub_f32_e32 v82, v82, v216
	v_sub_f32_e32 v83, v83, v216
	v_sub_f32_e32 v84, v84, v216
	v_sub_f32_e32 v85, v85, v216
	v_sub_f32_e32 v114, v114, v216
	v_sub_f32_e32 v115, v115, v216
	v_sub_f32_e32 v116, v116, v216
	v_sub_f32_e32 v117, v117, v216
	v_sub_f32_e32 v118, v118, v216
	v_sub_f32_e32 v119, v119, v216
	v_sub_f32_e32 v120, v120, v216
	v_sub_f32_e32 v121, v121, v216
	v_sub_f32_e32 v122, v122, v216
	v_sub_f32_e32 v123, v123, v216
	v_sub_f32_e32 v124, v124, v216
	v_sub_f32_e32 v125, v125, v216
	v_sub_f32_e32 v126, v126, v216
	v_sub_f32_e32 v127, v127, v216
	v_sub_f32_e32 v128, v128, v216
	v_sub_f32_e32 v129, v129, v216
	v_sub_f32_e32 v130, v130, v216
	v_sub_f32_e32 v131, v131, v216
	v_sub_f32_e32 v132, v132, v216
	v_sub_f32_e32 v133, v133, v216
	v_mul_f32_e32 v213, v213, v217
	v_mul_f32_e32 v214, v214, v217
	v_mul_f32_e32 v2, v2, v217
	v_mul_f32_e32 v3, v3, v217
	v_mul_f32_e32 v4, v4, v217
	v_mul_f32_e32 v5, v5, v217
	v_mul_f32_e32 v6, v6, v217
	v_mul_f32_e32 v7, v7, v217
	v_mul_f32_e32 v8, v8, v217
	v_mul_f32_e32 v9, v9, v217
	v_mul_f32_e32 v10, v10, v217
	v_mul_f32_e32 v11, v11, v217
	v_mul_f32_e32 v12, v12, v217
	v_mul_f32_e32 v13, v13, v217
	v_mul_f32_e32 v14, v14, v217
	v_mul_f32_e32 v15, v15, v217
	v_mul_f32_e32 v16, v16, v217
	v_mul_f32_e32 v17, v17, v217
	v_mul_f32_e32 v18, v18, v217
	v_mul_f32_e32 v19, v19, v217
	v_mul_f32_e32 v20, v20, v217
	v_mul_f32_e32 v21, v21, v217
	v_mul_f32_e32 v22, v22, v217
	v_mul_f32_e32 v23, v23, v217
	v_mul_f32_e32 v24, v24, v217
	v_mul_f32_e32 v25, v25, v217
	v_mul_f32_e32 v26, v26, v217
	v_mul_f32_e32 v27, v27, v217
	v_mul_f32_e32 v28, v28, v217
	v_mul_f32_e32 v29, v29, v217
	v_mul_f32_e32 v30, v30, v217
	v_mul_f32_e32 v31, v31, v217
	v_mul_f32_e32 v32, v32, v217
	v_mul_f32_e32 v33, v33, v217
	v_mov_b32_e32 v220, 0
	v_mov_b32_e32 v221, -1
	s_mov_b64 s[26:27], 0

.Lna_done_w0:
	s_add_i32 s24, s24, 1
	s_add_i32 s25, s25, 0x150
	s_add_i32 s33, s33, -1
	s_cmp_lg_u32 s33, 0
	s_cbranch_scc1 .Lna_wloop
	v_sub_f32_e32 v114, 0, v212
	v_mov_b32_e32 v115, v114
	v_mov_b32_e32 v116, v114
	v_mov_b32_e32 v117, v114
	v_mov_b32_e32 v118, v114
	v_mov_b32_e32 v119, v114
	v_mov_b32_e32 v120, v114
	v_mov_b32_e32 v121, v114
	v_mov_b32_e32 v122, v114
	v_mov_b32_e32 v123, v114
	v_mov_b32_e32 v124, v114
	v_mov_b32_e32 v125, v114
	v_mov_b32_e32 v126, v114
	v_mov_b32_e32 v127, v114
	v_mov_b32_e32 v128, v114
	v_mov_b32_e32 v129, v114
	v_mov_b32_e32 v130, v114
	v_mov_b32_e32 v131, v114
	v_mov_b32_e32 v132, v114
	v_mov_b32_e32 v133, v114
	v_mov_b32_e32 v134, v114
	v_mov_b32_e32 v135, v114
	v_mov_b32_e32 v136, v114
	v_mov_b32_e32 v137, v114
	v_mov_b32_e32 v138, v114
	v_mov_b32_e32 v139, v114
	v_mov_b32_e32 v140, v114
	v_mov_b32_e32 v141, v114
	v_mov_b32_e32 v142, v114
	v_mov_b32_e32 v143, v114
	v_mov_b32_e32 v144, v114
	v_mov_b32_e32 v145, v114
	s_sub_i32 s36, s24, s23
	s_cmp_lt_u32 s36, 8
	s_cselect_b64 s[40:41], -1, 0
	s_mov_b64 s[42:43], -1
	s_cmp_eq_u64 s[40:41], 0
	s_cbranch_scc1 .Lna_slow_wc
	ds_read_b128 v[146:149], v199 offset:0
	ds_read_b128 v[150:153], v200 offset:0
	ds_read_b128 v[154:157], v199 offset:32
	ds_read_b128 v[158:161], v200 offset:32
	v_exp_f32_e32 v66, v66
	v_exp_f32_e32 v67, v67
	v_exp_f32_e32 v68, v68
	v_exp_f32_e32 v69, v69
	s_waitcnt lgkmcnt(2)
	v_mfma_f32_32x32x16_bf16 v[34:49], v[146:149], v[98:101], v[114:129]
	ds_read_b128 v[146:149], v199 offset:64
	v_add_f32_e32 v213, v213, v66
	v_add_f32_e32 v214, v214, v67
	v_add_f32_e32 v213, v213, v68
	v_add_f32_e32 v214, v214, v69
	v_exp_f32_e32 v70, v70
	v_mfma_f32_32x32x16_bf16 v[50:65], v[150:153], v[98:101], v[130:145]
	ds_read_b128 v[150:153], v200 offset:64
	v_exp_f32_e32 v71, v71
	v_exp_f32_e32 v72, v72
	v_exp_f32_e32 v73, v73
	s_waitcnt lgkmcnt(2)
	v_mfma_f32_32x32x16_bf16 v[34:49], v[154:157], v[102:105], v[34:49]
	ds_read_b128 v[154:157], v199 offset:96
	v_add_f32_e32 v213, v213, v70
	v_add_f32_e32 v214, v214, v71
	v_add_f32_e32 v213, v213, v72
	v_add_f32_e32 v214, v214, v73
	v_cvt_pk_bf16_f32 v66, v66, v67
	v_mfma_f32_32x32x16_bf16 v[50:65], v[158:161], v[102:105], v[50:65]
	ds_read_b128 v[158:161], v200 offset:96
	v_cvt_pk_bf16_f32 v67, v68, v69
	v_cvt_pk_bf16_f32 v68, v70, v71
	v_cvt_pk_bf16_f32 v69, v72, v73
	v_exp_f32_e32 v74, v74
	v_exp_f32_e32 v75, v75
	s_waitcnt lgkmcnt(2)
	v_mfma_f32_32x32x16_bf16 v[34:49], v[146:149], v[106:109], v[34:49]
	ds_read_b64 v[162:163], v201 offset:8704
	ds_read_b64 v[164:165], v201 offset:8720
	v_exp_f32_e32 v76, v76
	v_exp_f32_e32 v77, v77
	v_add_f32_e32 v213, v213, v74
	v_mfma_f32_32x32x16_bf16 v[50:65], v[150:153], v[106:109], v[50:65]
	ds_read_b64 v[166:167], v201 offset:13056
	ds_read_b64 v[168:169], v201 offset:13072
	v_add_f32_e32 v214, v214, v75
	v_add_f32_e32 v213, v213, v76
	v_add_f32_e32 v214, v214, v77
	v_exp_f32_e32 v78, v78
	v_exp_f32_e32 v79, v79
	s_waitcnt lgkmcnt(4)
	v_mfma_f32_32x32x16_bf16 v[34:49], v[154:157], v[110:113], v[34:49]
	ds_read_b64 v[170:171], v201 offset:8736
	ds_read_b64 v[172:173], v201 offset:8752
	v_exp_f32_e32 v80, v80
	v_exp_f32_e32 v81, v81
	v_add_f32_e32 v213, v213, v78
	v_add_f32_e32 v214, v214, v79
	v_mfma_f32_32x32x16_bf16 v[50:65], v[158:161], v[110:113], v[50:65]
	ds_read_b64 v[174:175], v201 offset:13088
	ds_read_b64 v[176:177], v201 offset:13104
	v_add_f32_e32 v213, v213, v80
	v_add_f32_e32 v214, v214, v81
	v_cvt_pk_bf16_f32 v74, v74, v75
	v_cvt_pk_bf16_f32 v75, v76, v77
	v_cvt_pk_bf16_f32 v76, v78, v79
	v_cvt_pk_bf16_f32 v77, v80, v81
	s_waitcnt lgkmcnt(6)
	v_mfma_f32_32x32x16_bf16 v[2:17], v[162:165], v[66:69], v[2:17]
	ds_read_b64 v[162:163], v202 offset:8704
	ds_read_b64 v[164:165], v203 offset:8704
	v_exp_f32_e32 v82, v82
	v_exp_f32_e32 v83, v83
	v_exp_f32_e32 v84, v84
	s_waitcnt lgkmcnt(6)
	v_mfma_f32_32x32x16_bf16 v[18:33], v[166:169], v[66:69], v[18:33]
	ds_read_b64 v[166:167], v202 offset:13056
	ds_read_b64 v[168:169], v203 offset:13056
	v_exp_f32_e32 v85, v85
	v_add_f32_e32 v213, v213, v82
	v_add_f32_e32 v214, v214, v83
	v_add_f32_e32 v213, v213, v84
	v_add_f32_e32 v214, v214, v85
	s_waitcnt lgkmcnt(6)
	v_mfma_f32_32x32x16_bf16 v[2:17], v[170:173], v[74:77], v[2:17]
	v_cvt_pk_bf16_f32 v184, v82, v83
	v_cvt_pk_bf16_f32 v185, v84, v85
	v_max3_f32 v216, v34, v35, v36
	v_max3_f32 v217, v50, v51, v52
	v_max3_f32 v216, v216, v37, v38
	v_max3_f32 v217, v217, v53, v54
	s_waitcnt lgkmcnt(4)
	v_mfma_f32_32x32x16_bf16 v[18:33], v[174:177], v[74:77], v[18:33]
	s_waitcnt vmcnt(2)
	ds_write_b128 v204, v[230:233] offset:9216
	ds_write_b64 v205, v[234:235] offset:0
	ds_write_b64 v205, v[236:237] offset:8
	global_load_dwordx4 v[230:233], v206, s[12:13]
	s_add_u32 s12, s12, 0x2000
	s_addc_u32 s13, s13, 0
	global_load_dwordx4 v[234:237], v207, s[14:15]
	s_add_u32 s14, s14, 0x80
	s_addc_u32 s15, s15, 0
	v_max3_f32 v216, v216, v39, v40
	v_max3_f32 v217, v217, v55, v56
	v_max3_f32 v216, v216, v41, v42
	v_max3_f32 v217, v217, v57, v58
	v_max3_f32 v216, v216, v43, v44
	v_max3_f32 v217, v217, v59, v60
	s_waitcnt lgkmcnt(5)
	v_mfma_f32_32x32x16_bf16 v[2:17], v[162:165], v[184:187], v[2:17]
	v_max3_f32 v216, v216, v45, v46
	v_max3_f32 v217, v217, v61, v62
	v_max3_f32 v216, v216, v47, v48
	v_max3_f32 v217, v217, v63, v64
	v_max_f32_e32 v216, v216, v49
	v_max_f32_e32 v217, v217, v65
	s_waitcnt lgkmcnt(3)
	v_mfma_f32_32x32x16_bf16 v[18:33], v[166:169], v[184:187], v[18:33]
	v_max_f32_e32 v216, v216, v217
	v_mov_b32_e32 v217, v216
	s_nop 1
	v_permlane32_swap_b32_e32 v216, v217
	v_max_f32_e32 v215, v216, v217
	v_cmp_lt_f32_e32 vcc, 4.0, v215
	s_cbranch_vccz .Lna_nr_wcf
	s_nop 15
	v_max_f32_e32 v216, v215, v220
	v_exp_f32_e64 v217, -v216
	v_add_f32_e32 v212, v212, v216
	v_and_b32_e32 v217, v217, v221
	v_sub_f32_e32 v34, v34, v216
	v_sub_f32_e32 v35, v35, v216
	v_sub_f32_e32 v36, v36, v216
	v_sub_f32_e32 v37, v37, v216
	v_sub_f32_e32 v38, v38, v216
	v_sub_f32_e32 v39, v39, v216
	v_sub_f32_e32 v40, v40, v216
	v_sub_f32_e32 v41, v41, v216
	v_sub_f32_e32 v42, v42, v216
	v_sub_f32_e32 v43, v43, v216
	v_sub_f32_e32 v44, v44, v216
	v_sub_f32_e32 v45, v45, v216
	v_sub_f32_e32 v46, v46, v216
	v_sub_f32_e32 v47, v47, v216
	v_sub_f32_e32 v48, v48, v216
	v_sub_f32_e32 v49, v49, v216
	v_sub_f32_e32 v50, v50, v216
	v_sub_f32_e32 v51, v51, v216
	v_sub_f32_e32 v52, v52, v216
	v_sub_f32_e32 v53, v53, v216
	v_sub_f32_e32 v54, v54, v216
	v_sub_f32_e32 v55, v55, v216
	v_sub_f32_e32 v56, v56, v216
	v_sub_f32_e32 v57, v57, v216
	v_sub_f32_e32 v58, v58, v216
	v_sub_f32_e32 v59, v59, v216
	v_sub_f32_e32 v60, v60, v216
	v_sub_f32_e32 v61, v61, v216
	v_sub_f32_e32 v62, v62, v216
	v_sub_f32_e32 v63, v63, v216
	v_sub_f32_e32 v64, v64, v216
	v_sub_f32_e32 v65, v65, v216
	v_sub_f32_e32 v114, v114, v216
	v_sub_f32_e32 v115, v115, v216
	v_sub_f32_e32 v116, v116, v216
	v_sub_f32_e32 v117, v117, v216
	v_sub_f32_e32 v118, v118, v216
	v_sub_f32_e32 v119, v119, v216
	v_sub_f32_e32 v120, v120, v216
	v_sub_f32_e32 v121, v121, v216
	v_sub_f32_e32 v122, v122, v216
	v_sub_f32_e32 v123, v123, v216
	v_sub_f32_e32 v124, v124, v216
	v_sub_f32_e32 v125, v125, v216
	v_sub_f32_e32 v126, v126, v216
	v_sub_f32_e32 v127, v127, v216
	v_sub_f32_e32 v128, v128, v216
	v_sub_f32_e32 v129, v129, v216
	v_sub_f32_e32 v130, v130, v216
	v_sub_f32_e32 v131, v131, v216
	v_sub_f32_e32 v132, v132, v216
	v_sub_f32_e32 v133, v133, v216
	v_sub_f32_e32 v134, v134, v216
	v_sub_f32_e32 v135, v135, v216
	v_sub_f32_e32 v136, v136, v216
	v_sub_f32_e32 v137, v137, v216
	v_sub_f32_e32 v138, v138, v216
	v_sub_f32_e32 v139, v139, v216
	v_sub_f32_e32 v140, v140, v216
	v_sub_f32_e32 v141, v141, v216
	v_sub_f32_e32 v142, v142, v216
	v_sub_f32_e32 v143, v143, v216
	v_sub_f32_e32 v144, v144, v216
	v_sub_f32_e32 v145, v145, v216
	v_mul_f32_e32 v213, v213, v217
	v_mul_f32_e32 v214, v214, v217
	v_mul_f32_e32 v2, v2, v217
	v_mul_f32_e32 v3, v3, v217
	v_mul_f32_e32 v4, v4, v217
	v_mul_f32_e32 v5, v5, v217
	v_mul_f32_e32 v6, v6, v217
	v_mul_f32_e32 v7, v7, v217
	v_mul_f32_e32 v8, v8, v217
	v_mul_f32_e32 v9, v9, v217
	v_mul_f32_e32 v10, v10, v217
	v_mul_f32_e32 v11, v11, v217
	v_mul_f32_e32 v12, v12, v217
	v_mul_f32_e32 v13, v13, v217
	v_mul_f32_e32 v14, v14, v217
	v_mul_f32_e32 v15, v15, v217
	v_mul_f32_e32 v16, v16, v217
	v_mul_f32_e32 v17, v17, v217
	v_mul_f32_e32 v18, v18, v217
	v_mul_f32_e32 v19, v19, v217
	v_mul_f32_e32 v20, v20, v217
	v_mul_f32_e32 v21, v21, v217
	v_mul_f32_e32 v22, v22, v217
	v_mul_f32_e32 v23, v23, v217
	v_mul_f32_e32 v24, v24, v217
	v_mul_f32_e32 v25, v25, v217
	v_mul_f32_e32 v26, v26, v217
	v_mul_f32_e32 v27, v27, v217
	v_mul_f32_e32 v28, v28, v217
	v_mul_f32_e32 v29, v29, v217
	v_mul_f32_e32 v30, v30, v217
	v_mul_f32_e32 v31, v31, v217
	v_mul_f32_e32 v32, v32, v217
	v_mul_f32_e32 v33, v33, v217

.Lna_done_wc:
	ds_read_b128 v[146:149], v199 offset:9216
	ds_read_b128 v[150:153], v200 offset:9216
	ds_read_b128 v[154:157], v199 offset:9248
	ds_read_b128 v[158:161], v200 offset:9248
	v_exp_f32_e32 v34, v34
	v_exp_f32_e32 v35, v35
	v_exp_f32_e32 v36, v36
	v_exp_f32_e32 v37, v37
	s_waitcnt lgkmcnt(2)
	v_mfma_f32_32x32x16_bf16 v[66:81], v[146:149], v[98:101], v[114:129]
	ds_read_b128 v[146:149], v199 offset:9280
	v_add_f32_e32 v213, v213, v34
	v_add_f32_e32 v214, v214, v35
	v_add_f32_e32 v213, v213, v36
	v_add_f32_e32 v214, v214, v37
	v_exp_f32_e32 v38, v38
	v_exp_f32_e32 v39, v39
	v_mfma_f32_32x32x16_bf16 v[82:97], v[150:153], v[98:101], v[130:145]
	ds_read_b128 v[150:153], v200 offset:9280
	v_exp_f32_e32 v40, v40
	v_exp_f32_e32 v41, v41
	v_add_f32_e32 v213, v213, v38
	v_add_f32_e32 v214, v214, v39
	v_add_f32_e32 v213, v213, v40
	v_add_f32_e32 v214, v214, v41
	s_waitcnt lgkmcnt(2)
	v_mfma_f32_32x32x16_bf16 v[66:81], v[154:157], v[102:105], v[66:81]
	ds_read_b128 v[154:157], v199 offset:9312
	v_cvt_pk_bf16_f32 v34, v34, v35
	v_cvt_pk_bf16_f32 v35, v36, v37
	v_cvt_pk_bf16_f32 v36, v38, v39
	v_cvt_pk_bf16_f32 v37, v40, v41
	v_exp_f32_e32 v42, v42
	v_exp_f32_e32 v43, v43
	v_mfma_f32_32x32x16_bf16 v[82:97], v[158:161], v[102:105], v[82:97]
	ds_read_b128 v[158:161], v200 offset:9312
	v_exp_f32_e32 v44, v44
	v_exp_f32_e32 v45, v45
	v_add_f32_e32 v213, v213, v42
	v_add_f32_e32 v214, v214, v43
	v_add_f32_e32 v213, v213, v44
	v_add_f32_e32 v214, v214, v45
	s_waitcnt lgkmcnt(2)
	v_mfma_f32_32x32x16_bf16 v[66:81], v[146:149], v[106:109], v[66:81]
	ds_read_b64 v[162:163], v201 offset:0
	ds_read_b64 v[164:165], v201 offset:16
	v_exp_f32_e32 v46, v46
	v_exp_f32_e32 v47, v47
	v_exp_f32_e32 v48, v48
	v_exp_f32_e32 v49, v49
	v_mfma_f32_32x32x16_bf16 v[82:97], v[150:153], v[106:109], v[82:97]
	ds_read_b64 v[166:167], v201 offset:4352
	ds_read_b64 v[168:169], v201 offset:4368
	v_add_f32_e32 v213, v213, v46
	v_add_f32_e32 v214, v214, v47
	v_add_f32_e32 v213, v213, v48
	v_add_f32_e32 v214, v214, v49
	v_cvt_pk_bf16_f32 v42, v42, v43
	v_cvt_pk_bf16_f32 v43, v44, v45
	v_cvt_pk_bf16_f32 v44, v46, v47
	v_cvt_pk_bf16_f32 v45, v48, v49
	s_waitcnt lgkmcnt(4)
	v_mfma_f32_32x32x16_bf16 v[66:81], v[154:157], v[110:113], v[66:81]
	ds_read_b64 v[170:171], v201 offset:32
	ds_read_b64 v[172:173], v201 offset:48
	v_exp_f32_e32 v50, v50
	v_exp_f32_e32 v51, v51
	v_exp_f32_e32 v52, v52
	v_exp_f32_e32 v53, v53
	v_mfma_f32_32x32x16_bf16 v[82:97], v[158:161], v[110:113], v[82:97]
	ds_read_b64 v[174:175], v201 offset:4384
	ds_read_b64 v[176:177], v201 offset:4400
	v_add_f32_e32 v213, v213, v50
	v_add_f32_e32 v214, v214, v51
	v_add_f32_e32 v213, v213, v52
	v_add_f32_e32 v214, v214, v53
	v_exp_f32_e32 v54, v54
	v_exp_f32_e32 v55, v55
	s_waitcnt lgkmcnt(6)
	v_mfma_f32_32x32x16_bf16 v[2:17], v[162:165], v[34:37], v[2:17]
	ds_read_b64 v[162:163], v202 offset:0
	ds_read_b64 v[164:165], v203 offset:0
	v_exp_f32_e32 v56, v56
	v_exp_f32_e32 v57, v57
	v_add_f32_e32 v213, v213, v54
	v_add_f32_e32 v214, v214, v55
	v_add_f32_e32 v213, v213, v56
	s_waitcnt lgkmcnt(6)
	v_mfma_f32_32x32x16_bf16 v[18:33], v[166:169], v[34:37], v[18:33]
	ds_read_b64 v[166:167], v202 offset:4352
	ds_read_b64 v[168:169], v203 offset:4352
	v_add_f32_e32 v214, v214, v57
	v_cvt_pk_bf16_f32 v50, v50, v51
	v_cvt_pk_bf16_f32 v51, v52, v53
	v_cvt_pk_bf16_f32 v52, v54, v55
	v_cvt_pk_bf16_f32 v53, v56, v57
	v_exp_f32_e32 v58, v58
	v_exp_f32_e32 v59, v59
	s_waitcnt lgkmcnt(6)
	v_mfma_f32_32x32x16_bf16 v[2:17], v[170:173], v[42:45], v[2:17]
	ds_read_b64 v[170:171], v203 offset:16
	ds_read_b64 v[172:173], v203 offset:32
	v_exp_f32_e32 v60, v60
	v_exp_f32_e32 v61, v61
	v_add_f32_e32 v213, v213, v58
	v_add_f32_e32 v214, v214, v59
	v_add_f32_e32 v213, v213, v60
	s_waitcnt lgkmcnt(6)
	v_mfma_f32_32x32x16_bf16 v[18:33], v[174:177], v[42:45], v[18:33]
	ds_read_b64 v[174:175], v203 offset:4368
	ds_read_b64 v[176:177], v203 offset:4384
	s_waitcnt vmcnt(2)
	ds_write_b128 v204, v[188:191] offset:0
	ds_write_b64 v205, v[192:193] offset:8704
	ds_write_b64 v205, v[194:195] offset:8712
	global_load_dwordx4 v[192:195], v207, s[14:15]
	s_add_u32 s14, s14, 0x80
	s_addc_u32 s15, s15, 0
	v_add_f32_e32 v214, v214, v61
	v_exp_f32_e32 v62, v62
	v_exp_f32_e32 v63, v63
	v_exp_f32_e32 v64, v64
	v_exp_f32_e32 v65, v65
	s_waitcnt lgkmcnt(9)
	v_mfma_f32_32x32x16_bf16 v[2:17], v[162:165], v[50:53], v[2:17]
	v_add_f32_e32 v213, v213, v62
	v_add_f32_e32 v214, v214, v63
	v_add_f32_e32 v213, v213, v64
	v_add_f32_e32 v214, v214, v65
	v_cvt_pk_bf16_f32 v58, v58, v59
	v_cvt_pk_bf16_f32 v59, v60, v61
	v_cvt_pk_bf16_f32 v60, v62, v63
	s_waitcnt lgkmcnt(7)
	v_mfma_f32_32x32x16_bf16 v[18:33], v[166:169], v[50:53], v[18:33]
	v_cvt_pk_bf16_f32 v61, v64, v65
	v_max3_f32 v216, v66, v67, v68
	v_max3_f32 v217, v82, v83, v84
	v_max3_f32 v216, v216, v69, v70
	v_max3_f32 v217, v217, v85, v86
	v_max3_f32 v216, v216, v71, v72
	v_max3_f32 v217, v217, v87, v88
	v_max3_f32 v216, v216, v73, v74
	s_waitcnt lgkmcnt(5)
	v_mfma_f32_32x32x16_bf16 v[2:17], v[170:173], v[58:61], v[2:17]
	v_max3_f32 v217, v217, v89, v90
	v_max3_f32 v216, v216, v75, v76
	v_max3_f32 v217, v217, v91, v92
	v_max3_f32 v216, v216, v77, v78
	v_max3_f32 v217, v217, v93, v94
	v_max3_f32 v216, v216, v79, v80
	v_max3_f32 v217, v217, v95, v96
	v_max_f32_e32 v216, v216, v81
	s_waitcnt lgkmcnt(3)
	v_mfma_f32_32x32x16_bf16 v[18:33], v[174:177], v[58:61], v[18:33]
	v_max_f32_e32 v217, v217, v97
	v_max_f32_e32 v216, v216, v217
	v_mov_b32_e32 v217, v216
	s_nop 1
	v_permlane32_swap_b32_e32 v216, v217
	v_max_f32_e32 v215, v216, v217
	v_cmp_lt_f32_e32 vcc, 4.0, v215
	s_cbranch_vccz .Lna_nr_c0
	s_nop 15
	v_max_f32_e32 v216, v215, v220
	v_exp_f32_e64 v217, -v216
	v_add_f32_e32 v212, v212, v216
	v_and_b32_e32 v217, v217, v221
	v_sub_f32_e32 v66, v66, v216
	v_sub_f32_e32 v67, v67, v216
	v_sub_f32_e32 v68, v68, v216
	v_sub_f32_e32 v69, v69, v216
	v_sub_f32_e32 v70, v70, v216
	v_sub_f32_e32 v71, v71, v216
	v_sub_f32_e32 v72, v72, v216
	v_sub_f32_e32 v73, v73, v216
	v_sub_f32_e32 v74, v74, v216
	v_sub_f32_e32 v75, v75, v216
	v_sub_f32_e32 v76, v76, v216
	v_sub_f32_e32 v77, v77, v216
	v_sub_f32_e32 v78, v78, v216
	v_sub_f32_e32 v79, v79, v216
	v_sub_f32_e32 v80, v80, v216
	v_sub_f32_e32 v81, v81, v216
	v_sub_f32_e32 v82, v82, v216
	v_sub_f32_e32 v83, v83, v216
	v_sub_f32_e32 v84, v84, v216
	v_sub_f32_e32 v85, v85, v216
	v_sub_f32_e32 v86, v86, v216
	v_sub_f32_e32 v87, v87, v216
	v_sub_f32_e32 v88, v88, v216
	v_sub_f32_e32 v89, v89, v216
	v_sub_f32_e32 v90, v90, v216
	v_sub_f32_e32 v91, v91, v216
	v_sub_f32_e32 v92, v92, v216
	v_sub_f32_e32 v93, v93, v216
	v_sub_f32_e32 v94, v94, v216
	v_sub_f32_e32 v95, v95, v216
	v_sub_f32_e32 v96, v96, v216
	v_sub_f32_e32 v97, v97, v216
	v_sub_f32_e32 v114, v114, v216
	v_sub_f32_e32 v115, v115, v216
	v_sub_f32_e32 v116, v116, v216
	v_sub_f32_e32 v117, v117, v216
	v_sub_f32_e32 v118, v118, v216
	v_sub_f32_e32 v119, v119, v216
	v_sub_f32_e32 v120, v120, v216
	v_sub_f32_e32 v121, v121, v216
	v_sub_f32_e32 v122, v122, v216
	v_sub_f32_e32 v123, v123, v216
	v_sub_f32_e32 v124, v124, v216
	v_sub_f32_e32 v125, v125, v216
	v_sub_f32_e32 v126, v126, v216
	v_sub_f32_e32 v127, v127, v216
	v_sub_f32_e32 v128, v128, v216
	v_sub_f32_e32 v129, v129, v216
	v_sub_f32_e32 v130, v130, v216
	v_sub_f32_e32 v131, v131, v216
	v_sub_f32_e32 v132, v132, v216
	v_sub_f32_e32 v133, v133, v216
	v_sub_f32_e32 v134, v134, v216
	v_sub_f32_e32 v135, v135, v216
	v_sub_f32_e32 v136, v136, v216
	v_sub_f32_e32 v137, v137, v216
	v_sub_f32_e32 v138, v138, v216
	v_sub_f32_e32 v139, v139, v216
	v_sub_f32_e32 v140, v140, v216
	v_sub_f32_e32 v141, v141, v216
	v_sub_f32_e32 v142, v142, v216
	v_sub_f32_e32 v143, v143, v216
	v_sub_f32_e32 v144, v144, v216
	v_sub_f32_e32 v145, v145, v216
	v_mul_f32_e32 v213, v213, v217
	v_mul_f32_e32 v214, v214, v217
	v_mul_f32_e32 v2, v2, v217
	v_mul_f32_e32 v3, v3, v217
	v_mul_f32_e32 v4, v4, v217
	v_mul_f32_e32 v5, v5, v217
	v_mul_f32_e32 v6, v6, v217
	v_mul_f32_e32 v7, v7, v217
	v_mul_f32_e32 v8, v8, v217
	v_mul_f32_e32 v9, v9, v217
	v_mul_f32_e32 v10, v10, v217
	v_mul_f32_e32 v11, v11, v217
	v_mul_f32_e32 v12, v12, v217
	v_mul_f32_e32 v13, v13, v217
	v_mul_f32_e32 v14, v14, v217
	v_mul_f32_e32 v15, v15, v217
	v_mul_f32_e32 v16, v16, v217
	v_mul_f32_e32 v17, v17, v217
	v_mul_f32_e32 v18, v18, v217
	v_mul_f32_e32 v19, v19, v217
	v_mul_f32_e32 v20, v20, v217
	v_mul_f32_e32 v21, v21, v217
	v_mul_f32_e32 v22, v22, v217
	v_mul_f32_e32 v23, v23, v217
	v_mul_f32_e32 v24, v24, v217
	v_mul_f32_e32 v25, v25, v217
	v_mul_f32_e32 v26, v26, v217
	v_mul_f32_e32 v27, v27, v217
	v_mul_f32_e32 v28, v28, v217
	v_mul_f32_e32 v29, v29, v217
	v_mul_f32_e32 v30, v30, v217
	v_mul_f32_e32 v31, v31, v217
	v_mul_f32_e32 v32, v32, v217
	v_mul_f32_e32 v33, v33, v217
.Lna_nr_c0:
	s_waitcnt lgkmcnt(0)
	s_barrier
	ds_read_b128 v[146:149], v199 offset:0
	ds_read_b128 v[150:153], v200 offset:0
	ds_read_b128 v[154:157], v199 offset:32
	ds_read_b128 v[158:161], v200 offset:32
	v_exp_f32_e32 v66, v66
	v_exp_f32_e32 v67, v67
	v_exp_f32_e32 v68, v68
	v_exp_f32_e32 v69, v69
	s_waitcnt lgkmcnt(2)
	v_mfma_f32_32x32x16_bf16 v[34:49], v[146:149], v[98:101], v[114:129]
	ds_read_b128 v[146:149], v199 offset:64
	v_add_f32_e32 v213, v213, v66
	v_add_f32_e32 v214, v214, v67
	v_add_f32_e32 v213, v213, v68
	v_add_f32_e32 v214, v214, v69
	v_exp_f32_e32 v70, v70
	v_exp_f32_e32 v71, v71
	v_mfma_f32_32x32x16_bf16 v[50:65], v[150:153], v[98:101], v[130:145]
	ds_read_b128 v[150:153], v200 offset:64
	v_exp_f32_e32 v72, v72
	v_exp_f32_e32 v73, v73
	v_add_f32_e32 v213, v213, v70
	v_add_f32_e32 v214, v214, v71
	v_add_f32_e32 v213, v213, v72
	v_add_f32_e32 v214, v214, v73
	s_waitcnt lgkmcnt(2)
	v_mfma_f32_32x32x16_bf16 v[34:49], v[154:157], v[102:105], v[34:49]
	ds_read_b128 v[154:157], v199 offset:96
	v_cvt_pk_bf16_f32 v66, v66, v67
	v_cvt_pk_bf16_f32 v67, v68, v69
	v_cvt_pk_bf16_f32 v68, v70, v71
	v_cvt_pk_bf16_f32 v69, v72, v73
	v_exp_f32_e32 v74, v74
	v_exp_f32_e32 v75, v75
	v_mfma_f32_32x32x16_bf16 v[50:65], v[158:161], v[102:105], v[50:65]
	ds_read_b128 v[158:161], v200 offset:96
	v_exp_f32_e32 v76, v76
	v_exp_f32_e32 v77, v77
	v_add_f32_e32 v213, v213, v74
	v_add_f32_e32 v214, v214, v75
	v_add_f32_e32 v213, v213, v76
	v_add_f32_e32 v214, v214, v77
	s_waitcnt lgkmcnt(2)
	v_mfma_f32_32x32x16_bf16 v[34:49], v[146:149], v[106:109], v[34:49]
	ds_read_b64 v[162:163], v201 offset:8704
	ds_read_b64 v[164:165], v201 offset:8720
	v_exp_f32_e32 v78, v78
	v_exp_f32_e32 v79, v79
	v_exp_f32_e32 v80, v80
	v_exp_f32_e32 v81, v81
	v_mfma_f32_32x32x16_bf16 v[50:65], v[150:153], v[106:109], v[50:65]
	ds_read_b64 v[166:167], v201 offset:13056
	ds_read_b64 v[168:169], v201 offset:13072
	v_add_f32_e32 v213, v213, v78
	v_add_f32_e32 v214, v214, v79
	v_add_f32_e32 v213, v213, v80
	v_add_f32_e32 v214, v214, v81
	v_cvt_pk_bf16_f32 v74, v74, v75
	v_cvt_pk_bf16_f32 v75, v76, v77
	v_cvt_pk_bf16_f32 v76, v78, v79
	v_cvt_pk_bf16_f32 v77, v80, v81
	s_waitcnt lgkmcnt(4)
	v_mfma_f32_32x32x16_bf16 v[34:49], v[154:157], v[110:113], v[34:49]
	ds_read_b64 v[170:171], v201 offset:8736
	ds_read_b64 v[172:173], v201 offset:8752
	v_exp_f32_e32 v82, v82
	v_exp_f32_e32 v83, v83
	v_exp_f32_e32 v84, v84
	v_exp_f32_e32 v85, v85
	v_mfma_f32_32x32x16_bf16 v[50:65], v[158:161], v[110:113], v[50:65]
	ds_read_b64 v[174:175], v201 offset:13088
	ds_read_b64 v[176:177], v201 offset:13104
	v_add_f32_e32 v213, v213, v82
	v_add_f32_e32 v214, v214, v83
	v_add_f32_e32 v213, v213, v84
	v_add_f32_e32 v214, v214, v85
	v_exp_f32_e32 v86, v86
	v_exp_f32_e32 v87, v87
	s_waitcnt lgkmcnt(6)
	v_mfma_f32_32x32x16_bf16 v[2:17], v[162:165], v[66:69], v[2:17]
	ds_read_b64 v[162:163], v202 offset:8704
	ds_read_b64 v[164:165], v203 offset:8704
	v_exp_f32_e32 v88, v88
	v_exp_f32_e32 v89, v89
	v_add_f32_e32 v213, v213, v86
	v_add_f32_e32 v214, v214, v87
	v_add_f32_e32 v213, v213, v88
	s_waitcnt lgkmcnt(6)
	v_mfma_f32_32x32x16_bf16 v[18:33], v[166:169], v[66:69], v[18:33]
	ds_read_b64 v[166:167], v202 offset:13056
	ds_read_b64 v[168:169], v203 offset:13056
	v_add_f32_e32 v214, v214, v89
	v_cvt_pk_bf16_f32 v82, v82, v83
	v_cvt_pk_bf16_f32 v83, v84, v85
	v_cvt_pk_bf16_f32 v84, v86, v87
	v_cvt_pk_bf16_f32 v85, v88, v89
	v_exp_f32_e32 v90, v90
	v_exp_f32_e32 v91, v91
	s_waitcnt lgkmcnt(6)
	v_mfma_f32_32x32x16_bf16 v[2:17], v[170:173], v[74:77], v[2:17]
	ds_read_b64 v[170:171], v203 offset:8720
	ds_read_b64 v[172:173], v203 offset:8736
	v_exp_f32_e32 v92, v92
	v_exp_f32_e32 v93, v93
	v_add_f32_e32 v213, v213, v90
	v_add_f32_e32 v214, v214, v91
	v_add_f32_e32 v213, v213, v92
	s_waitcnt lgkmcnt(6)
	v_mfma_f32_32x32x16_bf16 v[18:33], v[174:177], v[74:77], v[18:33]
	ds_read_b64 v[174:175], v203 offset:13072
	ds_read_b64 v[176:177], v203 offset:13088
	s_waitcnt vmcnt(1)
	ds_write_b128 v204, v[230:233] offset:9216
	ds_write_b64 v205, v[234:235] offset:0
	ds_write_b64 v205, v[236:237] offset:8
	v_add_f32_e32 v214, v214, v93
	v_exp_f32_e32 v94, v94
	v_exp_f32_e32 v95, v95
	v_exp_f32_e32 v96, v96
	v_exp_f32_e32 v97, v97
	s_waitcnt lgkmcnt(9)
	v_mfma_f32_32x32x16_bf16 v[2:17], v[162:165], v[82:85], v[2:17]
	v_add_f32_e32 v213, v213, v94
	v_add_f32_e32 v214, v214, v95
	v_add_f32_e32 v213, v213, v96
	v_add_f32_e32 v214, v214, v97
	v_cvt_pk_bf16_f32 v90, v90, v91
	v_cvt_pk_bf16_f32 v91, v92, v93
	v_cvt_pk_bf16_f32 v92, v94, v95
	s_waitcnt lgkmcnt(7)
	v_mfma_f32_32x32x16_bf16 v[18:33], v[166:169], v[82:85], v[18:33]
	v_cvt_pk_bf16_f32 v93, v96, v97
	v_max3_f32 v216, v34, v35, v36
	v_max3_f32 v217, v50, v51, v52
	v_max3_f32 v216, v216, v37, v38
	v_max3_f32 v217, v217, v53, v54
	v_max3_f32 v216, v216, v39, v40
	v_max3_f32 v217, v217, v55, v56
	v_max3_f32 v216, v216, v41, v42
	s_waitcnt lgkmcnt(5)
	v_mfma_f32_32x32x16_bf16 v[2:17], v[170:173], v[90:93], v[2:17]
	v_max3_f32 v217, v217, v57, v58
	v_max3_f32 v216, v216, v43, v44
	v_max3_f32 v217, v217, v59, v60
	v_max3_f32 v216, v216, v45, v46
	v_max3_f32 v217, v217, v61, v62
	v_max3_f32 v216, v216, v47, v48
	v_max3_f32 v217, v217, v63, v64
	v_max_f32_e32 v216, v216, v49
	s_waitcnt lgkmcnt(3)
	v_mfma_f32_32x32x16_bf16 v[18:33], v[174:177], v[90:93], v[18:33]
	v_max_f32_e32 v217, v217, v65
	v_max_f32_e32 v216, v216, v217
	v_mov_b32_e32 v217, v216
	s_nop 1
	v_permlane32_swap_b32_e32 v216, v217
	v_max_f32_e32 v215, v216, v217
	v_cmp_lt_f32_e32 vcc, 4.0, v215
	s_cbranch_vccz .Lna_nr_c1
	s_nop 15
	v_max_f32_e32 v216, v215, v220
	v_exp_f32_e64 v217, -v216
	v_add_f32_e32 v212, v212, v216
	v_and_b32_e32 v217, v217, v221
	v_sub_f32_e32 v34, v34, v216
	v_sub_f32_e32 v35, v35, v216
	v_sub_f32_e32 v36, v36, v216
	v_sub_f32_e32 v37, v37, v216
	v_sub_f32_e32 v38, v38, v216
	v_sub_f32_e32 v39, v39, v216
	v_sub_f32_e32 v40, v40, v216
	v_sub_f32_e32 v41, v41, v216
	v_sub_f32_e32 v42, v42, v216
	v_sub_f32_e32 v43, v43, v216
	v_sub_f32_e32 v44, v44, v216
	v_sub_f32_e32 v45, v45, v216
	v_sub_f32_e32 v46, v46, v216
	v_sub_f32_e32 v47, v47, v216
	v_sub_f32_e32 v48, v48, v216
	v_sub_f32_e32 v49, v49, v216
	v_sub_f32_e32 v50, v50, v216
	v_sub_f32_e32 v51, v51, v216
	v_sub_f32_e32 v52, v52, v216
	v_sub_f32_e32 v53, v53, v216
	v_sub_f32_e32 v54, v54, v216
	v_sub_f32_e32 v55, v55, v216
	v_sub_f32_e32 v56, v56, v216
	v_sub_f32_e32 v57, v57, v216
	v_sub_f32_e32 v58, v58, v216
	v_sub_f32_e32 v59, v59, v216
	v_sub_f32_e32 v60, v60, v216
	v_sub_f32_e32 v61, v61, v216
	v_sub_f32_e32 v62, v62, v216
	v_sub_f32_e32 v63, v63, v216
	v_sub_f32_e32 v64, v64, v216
	v_sub_f32_e32 v65, v65, v216
	v_sub_f32_e32 v114, v114, v216
	v_sub_f32_e32 v115, v115, v216
	v_sub_f32_e32 v116, v116, v216
	v_sub_f32_e32 v117, v117, v216
	v_sub_f32_e32 v118, v118, v216
	v_sub_f32_e32 v119, v119, v216
	v_sub_f32_e32 v120, v120, v216
	v_sub_f32_e32 v121, v121, v216
	v_sub_f32_e32 v122, v122, v216
	v_sub_f32_e32 v123, v123, v216
	v_sub_f32_e32 v124, v124, v216
	v_sub_f32_e32 v125, v125, v216
	v_sub_f32_e32 v126, v126, v216
	v_sub_f32_e32 v127, v127, v216
	v_sub_f32_e32 v128, v128, v216
	v_sub_f32_e32 v129, v129, v216
	v_sub_f32_e32 v130, v130, v216
	v_sub_f32_e32 v131, v131, v216
	v_sub_f32_e32 v132, v132, v216
	v_sub_f32_e32 v133, v133, v216
	v_sub_f32_e32 v134, v134, v216
	v_sub_f32_e32 v135, v135, v216
	v_sub_f32_e32 v136, v136, v216
	v_sub_f32_e32 v137, v137, v216
	v_sub_f32_e32 v138, v138, v216
	v_sub_f32_e32 v139, v139, v216
	v_sub_f32_e32 v140, v140, v216
	v_sub_f32_e32 v141, v141, v216
	v_sub_f32_e32 v142, v142, v216
	v_sub_f32_e32 v143, v143, v216
	v_sub_f32_e32 v144, v144, v216
	v_sub_f32_e32 v145, v145, v216
	v_mul_f32_e32 v213, v213, v217
	v_mul_f32_e32 v214, v214, v217
	v_mul_f32_e32 v2, v2, v217
	v_mul_f32_e32 v3, v3, v217
	v_mul_f32_e32 v4, v4, v217
	v_mul_f32_e32 v5, v5, v217
	v_mul_f32_e32 v6, v6, v217
	v_mul_f32_e32 v7, v7, v217
	v_mul_f32_e32 v8, v8, v217
	v_mul_f32_e32 v9, v9, v217
	v_mul_f32_e32 v10, v10, v217
	v_mul_f32_e32 v11, v11, v217
	v_mul_f32_e32 v12, v12, v217
	v_mul_f32_e32 v13, v13, v217
	v_mul_f32_e32 v14, v14, v217
	v_mul_f32_e32 v15, v15, v217
	v_mul_f32_e32 v16, v16, v217
	v_mul_f32_e32 v17, v17, v217
	v_mul_f32_e32 v18, v18, v217
	v_mul_f32_e32 v19, v19, v217
	v_mul_f32_e32 v20, v20, v217
	v_mul_f32_e32 v21, v21, v217
	v_mul_f32_e32 v22, v22, v217
	v_mul_f32_e32 v23, v23, v217
	v_mul_f32_e32 v24, v24, v217
	v_mul_f32_e32 v25, v25, v217
	v_mul_f32_e32 v26, v26, v217
	v_mul_f32_e32 v27, v27, v217
	v_mul_f32_e32 v28, v28, v217
	v_mul_f32_e32 v29, v29, v217
	v_mul_f32_e32 v30, v30, v217
	v_mul_f32_e32 v31, v31, v217
	v_mul_f32_e32 v32, v32, v217
	v_mul_f32_e32 v33, v33, v217
.Lna_nr_c1:
	s_waitcnt lgkmcnt(0)
	s_barrier
	ds_read_b128 v[146:149], v199 offset:9216
	ds_read_b128 v[150:153], v200 offset:9216
	ds_read_b128 v[154:157], v199 offset:9248
	ds_read_b128 v[158:161], v200 offset:9248
	v_exp_f32_e32 v34, v34
	v_exp_f32_e32 v35, v35
	v_exp_f32_e32 v36, v36
	v_exp_f32_e32 v37, v37
	s_waitcnt lgkmcnt(2)
	v_mfma_f32_32x32x16_bf16 v[66:81], v[146:149], v[98:101], v[114:129]
	ds_read_b128 v[146:149], v199 offset:9280
	v_add_f32_e32 v213, v213, v34
	v_add_f32_e32 v214, v214, v35
	v_add_f32_e32 v213, v213, v36
	v_add_f32_e32 v214, v214, v37
	v_exp_f32_e32 v38, v38
	v_exp_f32_e32 v39, v39
	v_mfma_f32_32x32x16_bf16 v[82:97], v[150:153], v[98:101], v[130:145]
	ds_read_b128 v[150:153], v200 offset:9280
	v_exp_f32_e32 v40, v40
	v_exp_f32_e32 v41, v41
	v_add_f32_e32 v213, v213, v38
	v_add_f32_e32 v214, v214, v39
	v_add_f32_e32 v213, v213, v40
	v_add_f32_e32 v214, v214, v41
	s_waitcnt lgkmcnt(2)
	v_mfma_f32_32x32x16_bf16 v[66:81], v[154:157], v[102:105], v[66:81]
	ds_read_b128 v[154:157], v199 offset:9312
	v_cvt_pk_bf16_f32 v34, v34, v35
	v_cvt_pk_bf16_f32 v35, v36, v37
	v_cvt_pk_bf16_f32 v36, v38, v39
	v_cvt_pk_bf16_f32 v37, v40, v41
	v_exp_f32_e32 v42, v42
	v_exp_f32_e32 v43, v43
	v_mfma_f32_32x32x16_bf16 v[82:97], v[158:161], v[102:105], v[82:97]
	ds_read_b128 v[158:161], v200 offset:9312
	v_exp_f32_e32 v44, v44
	v_exp_f32_e32 v45, v45
	v_add_f32_e32 v213, v213, v42
	v_add_f32_e32 v214, v214, v43
	v_add_f32_e32 v213, v213, v44
	v_add_f32_e32 v214, v214, v45
	s_waitcnt lgkmcnt(2)
	v_mfma_f32_32x32x16_bf16 v[66:81], v[146:149], v[106:109], v[66:81]
	ds_read_b64 v[162:163], v201 offset:0
	ds_read_b64 v[164:165], v201 offset:16
	v_exp_f32_e32 v46, v46
	v_exp_f32_e32 v47, v47
	v_exp_f32_e32 v48, v48
	v_exp_f32_e32 v49, v49
	v_mfma_f32_32x32x16_bf16 v[82:97], v[150:153], v[106:109], v[82:97]
	ds_read_b64 v[166:167], v201 offset:4352
	ds_read_b64 v[168:169], v201 offset:4368
	v_add_f32_e32 v213, v213, v46
	v_add_f32_e32 v214, v214, v47
	v_add_f32_e32 v213, v213, v48
	v_add_f32_e32 v214, v214, v49
	v_cvt_pk_bf16_f32 v42, v42, v43
	v_cvt_pk_bf16_f32 v43, v44, v45
	v_cvt_pk_bf16_f32 v44, v46, v47
	v_cvt_pk_bf16_f32 v45, v48, v49
	s_waitcnt lgkmcnt(4)
	v_mfma_f32_32x32x16_bf16 v[66:81], v[154:157], v[110:113], v[66:81]
	ds_read_b64 v[170:171], v201 offset:32
	ds_read_b64 v[172:173], v201 offset:48
	v_exp_f32_e32 v50, v50
	v_exp_f32_e32 v51, v51
	v_exp_f32_e32 v52, v52
	v_exp_f32_e32 v53, v53
	v_mfma_f32_32x32x16_bf16 v[82:97], v[158:161], v[110:113], v[82:97]
	ds_read_b64 v[174:175], v201 offset:4384
	ds_read_b64 v[176:177], v201 offset:4400
	v_add_f32_e32 v213, v213, v50
	v_add_f32_e32 v214, v214, v51
	v_add_f32_e32 v213, v213, v52
	v_add_f32_e32 v214, v214, v53
	v_exp_f32_e32 v54, v54
	v_exp_f32_e32 v55, v55
	s_waitcnt lgkmcnt(6)
	v_mfma_f32_32x32x16_bf16 v[2:17], v[162:165], v[34:37], v[2:17]
	ds_read_b64 v[162:163], v202 offset:0
	ds_read_b64 v[164:165], v203 offset:0
	v_exp_f32_e32 v56, v56
	v_exp_f32_e32 v57, v57
	v_add_f32_e32 v213, v213, v54
	v_add_f32_e32 v214, v214, v55
	v_add_f32_e32 v213, v213, v56
	s_waitcnt lgkmcnt(6)
	v_mfma_f32_32x32x16_bf16 v[18:33], v[166:169], v[34:37], v[18:33]
	ds_read_b64 v[166:167], v202 offset:4352
	ds_read_b64 v[168:169], v203 offset:4352
	v_add_f32_e32 v214, v214, v57
	v_cvt_pk_bf16_f32 v50, v50, v51
	v_cvt_pk_bf16_f32 v51, v52, v53
	v_cvt_pk_bf16_f32 v52, v54, v55
	v_cvt_pk_bf16_f32 v53, v56, v57
	v_exp_f32_e32 v58, v58
	v_exp_f32_e32 v59, v59
	s_waitcnt lgkmcnt(6)
	v_mfma_f32_32x32x16_bf16 v[2:17], v[170:173], v[42:45], v[2:17]
	ds_read_b64 v[170:171], v203 offset:16
	ds_read_b64 v[172:173], v203 offset:32
	v_exp_f32_e32 v60, v60
	v_exp_f32_e32 v61, v61
	v_add_f32_e32 v213, v213, v58
	v_add_f32_e32 v214, v214, v59
	v_add_f32_e32 v213, v213, v60
	s_waitcnt lgkmcnt(6)
	v_mfma_f32_32x32x16_bf16 v[18:33], v[174:177], v[42:45], v[18:33]
	ds_read_b64 v[174:175], v203 offset:4368
	ds_read_b64 v[176:177], v203 offset:4384
	s_waitcnt vmcnt(0)
	ds_write_b64 v205, v[192:193] offset:8704
	ds_write_b64 v205, v[194:195] offset:8712
	v_add_f32_e32 v214, v214, v61
	v_exp_f32_e32 v62, v62
	v_exp_f32_e32 v63, v63
	v_exp_f32_e32 v64, v64
	v_exp_f32_e32 v65, v65
	s_waitcnt lgkmcnt(8)
	v_mfma_f32_32x32x16_bf16 v[2:17], v[162:165], v[50:53], v[2:17]
	v_add_f32_e32 v213, v213, v62
	v_add_f32_e32 v214, v214, v63
	v_add_f32_e32 v213, v213, v64
	v_add_f32_e32 v214, v214, v65
	v_cvt_pk_bf16_f32 v58, v58, v59
	v_cvt_pk_bf16_f32 v59, v60, v61
	v_cvt_pk_bf16_f32 v60, v62, v63
	s_waitcnt lgkmcnt(6)
	v_mfma_f32_32x32x16_bf16 v[18:33], v[166:169], v[50:53], v[18:33]
	v_cvt_pk_bf16_f32 v61, v64, v65
	v_max3_f32 v216, v66, v67, v68
	v_max3_f32 v217, v82, v83, v84
	v_max3_f32 v216, v216, v69, v70
	v_max3_f32 v217, v217, v85, v86
	v_max3_f32 v216, v216, v71, v72
	v_max3_f32 v217, v217, v87, v88
	v_max3_f32 v216, v216, v73, v74
	s_waitcnt lgkmcnt(4)
	v_mfma_f32_32x32x16_bf16 v[2:17], v[170:173], v[58:61], v[2:17]
	v_max3_f32 v217, v217, v89, v90
	v_max3_f32 v216, v216, v75, v76
	v_max3_f32 v217, v217, v91, v92
	v_max3_f32 v216, v216, v77, v78
	v_max3_f32 v217, v217, v93, v94
	v_max3_f32 v216, v216, v79, v80
	v_max3_f32 v217, v217, v95, v96
	v_max_f32_e32 v216, v216, v81
	s_waitcnt lgkmcnt(2)
	v_mfma_f32_32x32x16_bf16 v[18:33], v[174:177], v[58:61], v[18:33]
	v_max_f32_e32 v217, v217, v97
	v_max_f32_e32 v216, v216, v217
	v_mov_b32_e32 v217, v216
	s_nop 1
	v_permlane32_swap_b32_e32 v216, v217
	v_max_f32_e32 v215, v216, v217
	v_cmp_lt_f32_e32 vcc, 4.0, v215
	s_cbranch_vccz .Lna_nr_c2
	s_nop 15
	v_max_f32_e32 v216, v215, v220
	v_exp_f32_e64 v217, -v216
	v_add_f32_e32 v212, v212, v216
	v_and_b32_e32 v217, v217, v221
	v_sub_f32_e32 v66, v66, v216
	v_sub_f32_e32 v67, v67, v216
	v_sub_f32_e32 v68, v68, v216
	v_sub_f32_e32 v69, v69, v216
	v_sub_f32_e32 v70, v70, v216
	v_sub_f32_e32 v71, v71, v216
	v_sub_f32_e32 v72, v72, v216
	v_sub_f32_e32 v73, v73, v216
	v_sub_f32_e32 v74, v74, v216
	v_sub_f32_e32 v75, v75, v216
	v_sub_f32_e32 v76, v76, v216
	v_sub_f32_e32 v77, v77, v216
	v_sub_f32_e32 v78, v78, v216
	v_sub_f32_e32 v79, v79, v216
	v_sub_f32_e32 v80, v80, v216
	v_sub_f32_e32 v81, v81, v216
	v_sub_f32_e32 v82, v82, v216
	v_sub_f32_e32 v83, v83, v216
	v_sub_f32_e32 v84, v84, v216
	v_sub_f32_e32 v85, v85, v216
	v_sub_f32_e32 v86, v86, v216
	v_sub_f32_e32 v87, v87, v216
	v_sub_f32_e32 v88, v88, v216
	v_sub_f32_e32 v89, v89, v216
	v_sub_f32_e32 v90, v90, v216
	v_sub_f32_e32 v91, v91, v216
	v_sub_f32_e32 v92, v92, v216
	v_sub_f32_e32 v93, v93, v216
	v_sub_f32_e32 v94, v94, v216
	v_sub_f32_e32 v95, v95, v216
	v_sub_f32_e32 v96, v96, v216
	v_sub_f32_e32 v97, v97, v216
	v_sub_f32_e32 v114, v114, v216
	v_sub_f32_e32 v115, v115, v216
	v_sub_f32_e32 v116, v116, v216
	v_sub_f32_e32 v117, v117, v216
	v_sub_f32_e32 v118, v118, v216
	v_sub_f32_e32 v119, v119, v216
	v_sub_f32_e32 v120, v120, v216
	v_sub_f32_e32 v121, v121, v216
	v_sub_f32_e32 v122, v122, v216
	v_sub_f32_e32 v123, v123, v216
	v_sub_f32_e32 v124, v124, v216
	v_sub_f32_e32 v125, v125, v216
	v_sub_f32_e32 v126, v126, v216
	v_sub_f32_e32 v127, v127, v216
	v_sub_f32_e32 v128, v128, v216
	v_sub_f32_e32 v129, v129, v216
	v_sub_f32_e32 v130, v130, v216
	v_sub_f32_e32 v131, v131, v216
	v_sub_f32_e32 v132, v132, v216
	v_sub_f32_e32 v133, v133, v216
	v_sub_f32_e32 v134, v134, v216
	v_sub_f32_e32 v135, v135, v216
	v_sub_f32_e32 v136, v136, v216
	v_sub_f32_e32 v137, v137, v216
	v_sub_f32_e32 v138, v138, v216
	v_sub_f32_e32 v139, v139, v216
	v_sub_f32_e32 v140, v140, v216
	v_sub_f32_e32 v141, v141, v216
	v_sub_f32_e32 v142, v142, v216
	v_sub_f32_e32 v143, v143, v216
	v_sub_f32_e32 v144, v144, v216
	v_sub_f32_e32 v145, v145, v216
	v_mul_f32_e32 v213, v213, v217
	v_mul_f32_e32 v214, v214, v217
	v_mul_f32_e32 v2, v2, v217
	v_mul_f32_e32 v3, v3, v217
	v_mul_f32_e32 v4, v4, v217
	v_mul_f32_e32 v5, v5, v217
	v_mul_f32_e32 v6, v6, v217
	v_mul_f32_e32 v7, v7, v217
	v_mul_f32_e32 v8, v8, v217
	v_mul_f32_e32 v9, v9, v217
	v_mul_f32_e32 v10, v10, v217
	v_mul_f32_e32 v11, v11, v217
	v_mul_f32_e32 v12, v12, v217
	v_mul_f32_e32 v13, v13, v217
	v_mul_f32_e32 v14, v14, v217
	v_mul_f32_e32 v15, v15, v217
	v_mul_f32_e32 v16, v16, v217
	v_mul_f32_e32 v17, v17, v217
	v_mul_f32_e32 v18, v18, v217
	v_mul_f32_e32 v19, v19, v217
	v_mul_f32_e32 v20, v20, v217
	v_mul_f32_e32 v21, v21, v217
	v_mul_f32_e32 v22, v22, v217
	v_mul_f32_e32 v23, v23, v217
	v_mul_f32_e32 v24, v24, v217
	v_mul_f32_e32 v25, v25, v217
	v_mul_f32_e32 v26, v26, v217
	v_mul_f32_e32 v27, v27, v217
	v_mul_f32_e32 v28, v28, v217
	v_mul_f32_e32 v29, v29, v217
	v_mul_f32_e32 v30, v30, v217
	v_mul_f32_e32 v31, v31, v217
	v_mul_f32_e32 v32, v32, v217
	v_mul_f32_e32 v33, v33, v217

.Lmla_loop:
	v_exp_f32_e32 v34, v34
	v_exp_f32_e32 v35, v35
	v_exp_f32_e32 v36, v36
	v_exp_f32_e32 v37, v37
	s_waitcnt lgkmcnt(4)
	v_mfma_f32_32x32x16_bf16 v[66:81], v[138:141], v[98:101], v[122:137]
	ds_read_b128 v[138:141], v220 offset:13408
	v_add_f32_e32 v231, v231, v34
	v_add_f32_e32 v232, v232, v35
	v_exp_f32_e32 v38, v38
	v_exp_f32_e32 v39, v39
	v_mfma_f32_32x32x16_bf16 v[82:97], v[142:145], v[98:101], v[122:137]
	ds_read_b128 v[142:145], v220 offset:20064
	v_add_f32_e32 v231, v231, v36
	v_add_f32_e32 v232, v232, v37
	v_exp_f32_e32 v40, v40
	v_exp_f32_e32 v41, v41
	s_waitcnt lgkmcnt(4)
	v_mfma_f32_32x32x16_bf16 v[66:81], v[146:149], v[102:105], v[66:81]
	ds_read_b128 v[146:149], v220 offset:13440
	global_load_dwordx4 v[200:203], v226, s[4:5]
	global_load_dwordx4 v[204:207], v227, s[4:5]
	global_load_dwordx4 v[208:211], v228, s[4:5]
	s_add_u32 s4, s4, 0x6000
	s_addc_u32 s5, s5, 0
	global_load_dwordx4 v[212:215], v229, s[10:11]
	s_add_u32 s10, s10, 0x80
	s_addc_u32 s11, s11, 0
	v_add_f32_e32 v231, v231, v38
	v_add_f32_e32 v232, v232, v39
	v_add_f32_e32 v231, v231, v40
	v_add_f32_e32 v232, v232, v41
	v_cvt_pk_bf16_f32 v34, v34, v35
	v_cvt_pk_bf16_f32 v35, v36, v37
	v_mfma_f32_32x32x16_bf16 v[82:97], v[150:153], v[102:105], v[82:97]
	ds_read_b128 v[150:153], v220 offset:20096
	v_cvt_pk_bf16_f32 v36, v38, v39
	v_cvt_pk_bf16_f32 v37, v40, v41
	v_exp_f32_e32 v42, v42
	v_exp_f32_e32 v43, v43
	s_waitcnt lgkmcnt(4)
	v_mfma_f32_32x32x16_bf16 v[66:81], v[154:157], v[106:109], v[66:81]
	ds_read_b128 v[154:157], v220 offset:13472
	v_exp_f32_e32 v44, v44
	v_exp_f32_e32 v45, v45
	v_add_f32_e32 v231, v231, v42
	v_add_f32_e32 v232, v232, v43
	v_mfma_f32_32x32x16_bf16 v[82:97], v[158:161], v[106:109], v[82:97]
	ds_read_b128 v[158:161], v220 offset:20128
	v_exp_f32_e32 v46, v46
	v_exp_f32_e32 v47, v47
	v_add_f32_e32 v231, v231, v44
	v_add_f32_e32 v232, v232, v45
	v_exp_f32_e32 v48, v48
	s_waitcnt lgkmcnt(4)
	v_mfma_f32_32x32x16_bf16 v[66:81], v[138:141], v[110:113], v[66:81]
	ds_read_b64 v[162:163], v221 offset:0
	ds_read_b64 v[164:165], v221 offset:16
	v_exp_f32_e32 v49, v49
	v_add_f32_e32 v231, v231, v46
	v_add_f32_e32 v232, v232, v47
	v_add_f32_e32 v231, v231, v48
	v_mfma_f32_32x32x16_bf16 v[82:97], v[142:145], v[110:113], v[82:97]
	ds_read_b64 v[166:167], v221 offset:4352
	ds_read_b64 v[168:169], v221 offset:4368
	v_add_f32_e32 v232, v232, v49
	v_cvt_pk_bf16_f32 v42, v42, v43
	v_cvt_pk_bf16_f32 v43, v44, v45
	v_cvt_pk_bf16_f32 v44, v46, v47
	v_cvt_pk_bf16_f32 v45, v48, v49
	v_exp_f32_e32 v50, v50
	s_waitcnt lgkmcnt(6)
	v_mfma_f32_32x32x16_bf16 v[66:81], v[146:149], v[114:117], v[66:81]
	ds_read_b64 v[170:171], v221 offset:32
	ds_read_b64 v[172:173], v221 offset:48
	v_exp_f32_e32 v51, v51
	v_exp_f32_e32 v52, v52
	v_exp_f32_e32 v53, v53
	v_mfma_f32_32x32x16_bf16 v[82:97], v[150:153], v[114:117], v[82:97]
	ds_read_b64 v[174:175], v221 offset:4384
	ds_read_b64 v[176:177], v221 offset:4400
	v_add_f32_e32 v231, v231, v50
	v_add_f32_e32 v232, v232, v51
	v_exp_f32_e32 v54, v54
	v_exp_f32_e32 v55, v55
	s_waitcnt lgkmcnt(8)
	v_mfma_f32_32x32x16_bf16 v[66:81], v[154:157], v[118:121], v[66:81]
	ds_read_b64 v[180:181], v221 offset:64
	ds_read_b64 v[182:183], v221 offset:80
	v_add_f32_e32 v231, v231, v52
	v_add_f32_e32 v232, v232, v53
	v_exp_f32_e32 v56, v56
	v_exp_f32_e32 v57, v57
	v_mfma_f32_32x32x16_bf16 v[82:97], v[158:161], v[118:121], v[82:97]
	ds_read_b64 v[184:185], v221 offset:4416
	ds_read_b64 v[186:187], v221 offset:4432
	v_add_f32_e32 v231, v231, v54
	v_add_f32_e32 v232, v232, v55
	v_add_f32_e32 v231, v231, v56
	v_add_f32_e32 v232, v232, v57
	v_cvt_pk_bf16_f32 v50, v50, v51
	v_cvt_pk_bf16_f32 v51, v52, v53
	v_cvt_pk_bf16_f32 v52, v54, v55
	s_waitcnt lgkmcnt(8)
	v_mfma_f32_32x32x16_bf16 v[2:17], v[162:165], v[34:37], v[2:17]
	ds_read_b64 v[188:189], v221 offset:96
	ds_read_b64 v[190:191], v221 offset:112
	v_cvt_pk_bf16_f32 v53, v56, v57
	v_exp_f32_e32 v58, v58
	v_exp_f32_e32 v59, v59
	v_exp_f32_e32 v60, v60
	v_mfma_f32_32x32x16_bf16 v[18:33], v[166:169], v[34:37], v[18:33]
	ds_read_b64 v[192:193], v221 offset:4448
	ds_read_b64 v[194:195], v221 offset:4464
	v_exp_f32_e32 v61, v61
	v_add_f32_e32 v231, v231, v58
	v_add_f32_e32 v232, v232, v59
	v_exp_f32_e32 v62, v62
	s_waitcnt lgkmcnt(8)
	v_mfma_f32_32x32x16_bf16 v[2:17], v[170:173], v[42:45], v[2:17]
	v_exp_f32_e32 v63, v63
	v_add_f32_e32 v231, v231, v60
	v_add_f32_e32 v232, v232, v61
	v_exp_f32_e32 v64, v64
	v_mfma_f32_32x32x16_bf16 v[18:33], v[174:177], v[42:45], v[18:33]
	s_waitcnt vmcnt(4)
	ds_write_b64 v225, v[216:217] offset:17408
	ds_write_b64 v225, v[218:219] offset:17416
	v_exp_f32_e32 v65, v65
	v_add_f32_e32 v231, v231, v62
	v_add_f32_e32 v232, v232, v63
	v_add_f32_e32 v231, v231, v64
	v_add_f32_e32 v232, v232, v65
	s_waitcnt lgkmcnt(6)
	v_mfma_f32_32x32x16_bf16 v[2:17], v[180:183], v[50:53], v[2:17]
	v_cvt_pk_bf16_f32 v58, v58, v59
	v_cvt_pk_bf16_f32 v59, v60, v61
	v_cvt_pk_bf16_f32 v60, v62, v63
	v_cvt_pk_bf16_f32 v61, v64, v65
	v_max3_f32 v234, v66, v67, v68
	v_max3_f32 v235, v82, v83, v84
	v_mfma_f32_32x32x16_bf16 v[18:33], v[184:187], v[50:53], v[18:33]
	v_max3_f32 v234, v234, v69, v70
	v_max3_f32 v235, v235, v85, v86
	v_max3_f32 v234, v234, v71, v72
	v_max3_f32 v235, v235, v87, v88
	v_max3_f32 v234, v234, v73, v74
	v_max3_f32 v235, v235, v89, v90
	v_max3_f32 v234, v234, v75, v76
	s_waitcnt lgkmcnt(2)
	v_mfma_f32_32x32x16_bf16 v[2:17], v[188:191], v[58:61], v[2:17]
	v_max3_f32 v235, v235, v91, v92
	v_max3_f32 v234, v234, v77, v78
	v_max3_f32 v235, v235, v93, v94
	v_max3_f32 v234, v234, v79, v80
	v_max3_f32 v235, v235, v95, v96
	v_max3_f32 v234, v234, v81, v97
	v_mfma_f32_32x32x16_bf16 v[18:33], v[192:195], v[58:61], v[18:33]
	v_max_f32_e32 v234, v234, v235
	v_mov_b32_e32 v235, v234
	s_nop 1
	v_permlane32_swap_b32_e32 v234, v235
	v_max_f32_e32 v233, v234, v235
	v_cmp_lt_f32_e32 vcc, 4.0, v233
	s_cbranch_vccz .Lmla_nr_p0
	s_nop 15
	v_max_f32_e32 v234, 0, v233
	v_exp_f32_e64 v235, -v234
	v_add_f32_e32 v230, v230, v234
	v_sub_f32_e32 v66, v66, v234
	v_sub_f32_e32 v67, v67, v234
	v_sub_f32_e32 v68, v68, v234
	v_sub_f32_e32 v69, v69, v234
	v_sub_f32_e32 v70, v70, v234
	v_sub_f32_e32 v71, v71, v234
	v_sub_f32_e32 v72, v72, v234
	v_sub_f32_e32 v73, v73, v234
	v_sub_f32_e32 v74, v74, v234
	v_sub_f32_e32 v75, v75, v234
	v_sub_f32_e32 v76, v76, v234
	v_sub_f32_e32 v77, v77, v234
	v_sub_f32_e32 v78, v78, v234
	v_sub_f32_e32 v79, v79, v234
	v_sub_f32_e32 v80, v80, v234
	v_sub_f32_e32 v81, v81, v234
	v_sub_f32_e32 v82, v82, v234
	v_sub_f32_e32 v83, v83, v234
	v_sub_f32_e32 v84, v84, v234
	v_sub_f32_e32 v85, v85, v234
	v_sub_f32_e32 v86, v86, v234
	v_sub_f32_e32 v87, v87, v234
	v_sub_f32_e32 v88, v88, v234
	v_sub_f32_e32 v89, v89, v234
	v_sub_f32_e32 v90, v90, v234
	v_sub_f32_e32 v91, v91, v234
	v_sub_f32_e32 v92, v92, v234
	v_sub_f32_e32 v93, v93, v234
	v_sub_f32_e32 v94, v94, v234
	v_sub_f32_e32 v95, v95, v234
	v_sub_f32_e32 v96, v96, v234
	v_sub_f32_e32 v97, v97, v234
	v_mul_f32_e32 v231, v231, v235
	v_mul_f32_e32 v232, v232, v235
	v_mul_f32_e32 v2, v2, v235
	v_mul_f32_e32 v3, v3, v235
	v_mul_f32_e32 v4, v4, v235
	v_mul_f32_e32 v5, v5, v235
	v_mul_f32_e32 v6, v6, v235
	v_mul_f32_e32 v7, v7, v235
	v_mul_f32_e32 v8, v8, v235
	v_mul_f32_e32 v9, v9, v235
	v_mul_f32_e32 v10, v10, v235
	v_mul_f32_e32 v11, v11, v235
	v_mul_f32_e32 v12, v12, v235
	v_mul_f32_e32 v13, v13, v235
	v_mul_f32_e32 v14, v14, v235
	v_mul_f32_e32 v15, v15, v235
	v_mul_f32_e32 v16, v16, v235
	v_mul_f32_e32 v17, v17, v235
	v_mul_f32_e32 v18, v18, v235
	v_mul_f32_e32 v19, v19, v235
	v_mul_f32_e32 v20, v20, v235
	v_mul_f32_e32 v21, v21, v235
	v_mul_f32_e32 v22, v22, v235
	v_mul_f32_e32 v23, v23, v235
	v_mul_f32_e32 v24, v24, v235
	v_mul_f32_e32 v25, v25, v235
	v_mul_f32_e32 v26, v26, v235
	v_mul_f32_e32 v27, v27, v235
	v_mul_f32_e32 v28, v28, v235
	v_mul_f32_e32 v29, v29, v235
	v_mul_f32_e32 v30, v30, v235
	v_mul_f32_e32 v31, v31, v235
	v_mul_f32_e32 v32, v32, v235
	v_mul_f32_e32 v33, v33, v235
	v_sub_f32_e32 v122, 0, v230
	v_mov_b32_e32 v123, v122
	v_mov_b32_e32 v124, v122
	v_mov_b32_e32 v125, v122
	v_mov_b32_e32 v126, v122
	v_mov_b32_e32 v127, v122
	v_mov_b32_e32 v128, v122
	v_mov_b32_e32 v129, v122
	v_mov_b32_e32 v130, v122
	v_mov_b32_e32 v131, v122
	v_mov_b32_e32 v132, v122
	v_mov_b32_e32 v133, v122
	v_mov_b32_e32 v134, v122
	v_mov_b32_e32 v135, v122
	v_mov_b32_e32 v136, v122
	v_mov_b32_e32 v137, v122
.Lmla_nr_p0:
	ds_read_b128 v[138:141], v220 offset:26624
	ds_read_b128 v[142:145], v220 offset:33280
	ds_read_b128 v[146:149], v220 offset:26656
	ds_read_b128 v[150:153], v220 offset:33312
	ds_read_b128 v[154:157], v220 offset:26688
	ds_read_b128 v[158:161], v220 offset:33344
	s_waitcnt lgkmcnt(6)
	s_barrier
	v_exp_f32_e32 v66, v66
	v_exp_f32_e32 v67, v67
	v_exp_f32_e32 v68, v68
	v_exp_f32_e32 v69, v69
	s_waitcnt lgkmcnt(4)
	v_mfma_f32_32x32x16_bf16 v[34:49], v[138:141], v[98:101], v[122:137]
	ds_read_b128 v[138:141], v220 offset:26720
	v_add_f32_e32 v231, v231, v66
	v_add_f32_e32 v232, v232, v67
	v_exp_f32_e32 v70, v70
	v_exp_f32_e32 v71, v71
	v_mfma_f32_32x32x16_bf16 v[50:65], v[142:145], v[98:101], v[122:137]
	ds_read_b128 v[142:145], v220 offset:33376
	v_add_f32_e32 v231, v231, v68
	v_add_f32_e32 v232, v232, v69
	v_exp_f32_e32 v72, v72
	v_exp_f32_e32 v73, v73
	s_waitcnt lgkmcnt(4)
	v_mfma_f32_32x32x16_bf16 v[34:49], v[146:149], v[102:105], v[34:49]
	ds_read_b128 v[146:149], v220 offset:26752
	global_load_dwordx4 v[216:219], v229, s[10:11]
	s_add_u32 s10, s10, 0x80
	s_addc_u32 s11, s11, 0
	v_add_f32_e32 v231, v231, v70
	v_add_f32_e32 v232, v232, v71
	v_add_f32_e32 v231, v231, v72
	v_add_f32_e32 v232, v232, v73
	v_cvt_pk_bf16_f32 v66, v66, v67
	v_cvt_pk_bf16_f32 v67, v68, v69
	v_mfma_f32_32x32x16_bf16 v[50:65], v[150:153], v[102:105], v[50:65]
	ds_read_b128 v[150:153], v220 offset:33408
	v_cvt_pk_bf16_f32 v68, v70, v71
	v_cvt_pk_bf16_f32 v69, v72, v73
	v_exp_f32_e32 v74, v74
	v_exp_f32_e32 v75, v75
	s_waitcnt lgkmcnt(4)
	v_mfma_f32_32x32x16_bf16 v[34:49], v[154:157], v[106:109], v[34:49]
	ds_read_b128 v[154:157], v220 offset:26784
	v_exp_f32_e32 v76, v76
	v_exp_f32_e32 v77, v77
	v_add_f32_e32 v231, v231, v74
	v_add_f32_e32 v232, v232, v75
	v_mfma_f32_32x32x16_bf16 v[50:65], v[158:161], v[106:109], v[50:65]
	ds_read_b128 v[158:161], v220 offset:33440
	v_exp_f32_e32 v78, v78
	v_exp_f32_e32 v79, v79
	v_add_f32_e32 v231, v231, v76
	v_add_f32_e32 v232, v232, v77
	v_exp_f32_e32 v80, v80
	s_waitcnt lgkmcnt(4)
	v_mfma_f32_32x32x16_bf16 v[34:49], v[138:141], v[110:113], v[34:49]
	ds_read_b64 v[162:163], v221 offset:8704
	ds_read_b64 v[164:165], v221 offset:8720
	v_exp_f32_e32 v81, v81
	v_add_f32_e32 v231, v231, v78
	v_add_f32_e32 v232, v232, v79
	v_add_f32_e32 v231, v231, v80
	v_mfma_f32_32x32x16_bf16 v[50:65], v[142:145], v[110:113], v[50:65]
	ds_read_b64 v[166:167], v221 offset:13056
	ds_read_b64 v[168:169], v221 offset:13072
	v_add_f32_e32 v232, v232, v81
	v_cvt_pk_bf16_f32 v74, v74, v75
	v_cvt_pk_bf16_f32 v75, v76, v77
	v_cvt_pk_bf16_f32 v76, v78, v79
	v_cvt_pk_bf16_f32 v77, v80, v81
	v_exp_f32_e32 v82, v82
	s_waitcnt lgkmcnt(6)
	v_mfma_f32_32x32x16_bf16 v[34:49], v[146:149], v[114:117], v[34:49]
	ds_read_b64 v[170:171], v221 offset:8736
	ds_read_b64 v[172:173], v221 offset:8752
	v_exp_f32_e32 v83, v83
	v_exp_f32_e32 v84, v84
	v_exp_f32_e32 v85, v85
	v_mfma_f32_32x32x16_bf16 v[50:65], v[150:153], v[114:117], v[50:65]
	ds_read_b64 v[174:175], v221 offset:13088
	ds_read_b64 v[176:177], v221 offset:13104
	v_add_f32_e32 v231, v231, v82
	v_add_f32_e32 v232, v232, v83
	v_exp_f32_e32 v86, v86
	v_exp_f32_e32 v87, v87
	s_waitcnt lgkmcnt(8)
	v_mfma_f32_32x32x16_bf16 v[34:49], v[154:157], v[118:121], v[34:49]
	ds_read_b64 v[180:181], v221 offset:8768
	ds_read_b64 v[182:183], v221 offset:8784
	v_add_f32_e32 v231, v231, v84
	v_add_f32_e32 v232, v232, v85
	v_exp_f32_e32 v88, v88
	v_exp_f32_e32 v89, v89
	v_mfma_f32_32x32x16_bf16 v[50:65], v[158:161], v[118:121], v[50:65]
	ds_read_b64 v[184:185], v221 offset:13120
	ds_read_b64 v[186:187], v221 offset:13136
	v_add_f32_e32 v231, v231, v86
	v_add_f32_e32 v232, v232, v87
	v_add_f32_e32 v231, v231, v88
	v_add_f32_e32 v232, v232, v89
	v_cvt_pk_bf16_f32 v82, v82, v83
	v_cvt_pk_bf16_f32 v83, v84, v85
	v_cvt_pk_bf16_f32 v84, v86, v87
	s_waitcnt lgkmcnt(8)
	v_mfma_f32_32x32x16_bf16 v[2:17], v[162:165], v[66:69], v[2:17]
	ds_read_b64 v[188:189], v221 offset:8800
	ds_read_b64 v[190:191], v221 offset:8816
	v_cvt_pk_bf16_f32 v85, v88, v89
	v_exp_f32_e32 v90, v90
	v_exp_f32_e32 v91, v91
	v_exp_f32_e32 v92, v92
	v_mfma_f32_32x32x16_bf16 v[18:33], v[166:169], v[66:69], v[18:33]
	ds_read_b64 v[192:193], v221 offset:13152
	ds_read_b64 v[194:195], v221 offset:13168
	v_exp_f32_e32 v93, v93
	v_add_f32_e32 v231, v231, v90
	v_add_f32_e32 v232, v232, v91
	v_exp_f32_e32 v94, v94
	s_waitcnt lgkmcnt(8)
	v_mfma_f32_32x32x16_bf16 v[2:17], v[170:173], v[74:77], v[2:17]
	v_exp_f32_e32 v95, v95
	v_add_f32_e32 v231, v231, v92
	v_add_f32_e32 v232, v232, v93
	v_exp_f32_e32 v96, v96
	v_mfma_f32_32x32x16_bf16 v[18:33], v[174:177], v[74:77], v[18:33]
	s_waitcnt vmcnt(1)
	ds_write_b128 v222, v[200:203] offset:0
	ds_write_b128 v223, v[204:207] offset:0
	ds_write_b128 v224, v[208:211] offset:0
	ds_write_b64 v225, v[212:213] offset:26112
	ds_write_b64 v225, v[214:215] offset:26120
	v_exp_f32_e32 v97, v97
	v_add_f32_e32 v231, v231, v94
	v_add_f32_e32 v232, v232, v95
	v_add_f32_e32 v231, v231, v96
	v_add_f32_e32 v232, v232, v97
	s_waitcnt lgkmcnt(9)
	v_mfma_f32_32x32x16_bf16 v[2:17], v[180:183], v[82:85], v[2:17]
	v_cvt_pk_bf16_f32 v90, v90, v91
	v_cvt_pk_bf16_f32 v91, v92, v93
	v_cvt_pk_bf16_f32 v92, v94, v95
	v_cvt_pk_bf16_f32 v93, v96, v97
	v_max3_f32 v234, v34, v35, v36
	v_max3_f32 v235, v50, v51, v52
	v_mfma_f32_32x32x16_bf16 v[18:33], v[184:187], v[82:85], v[18:33]
	v_max3_f32 v234, v234, v37, v38
	v_max3_f32 v235, v235, v53, v54
	v_max3_f32 v234, v234, v39, v40
	v_max3_f32 v235, v235, v55, v56
	v_max3_f32 v234, v234, v41, v42
	v_max3_f32 v235, v235, v57, v58
	v_max3_f32 v234, v234, v43, v44
	s_waitcnt lgkmcnt(5)
	v_mfma_f32_32x32x16_bf16 v[2:17], v[188:191], v[90:93], v[2:17]
	v_max3_f32 v235, v235, v59, v60
	v_max3_f32 v234, v234, v45, v46
	v_max3_f32 v235, v235, v61, v62
	v_max3_f32 v234, v234, v47, v48
	v_max3_f32 v235, v235, v63, v64
	v_max3_f32 v234, v234, v49, v65
	v_mfma_f32_32x32x16_bf16 v[18:33], v[192:195], v[90:93], v[18:33]
	v_max_f32_e32 v234, v234, v235
	v_mov_b32_e32 v235, v234
	s_nop 1
	v_permlane32_swap_b32_e32 v234, v235
	v_max_f32_e32 v233, v234, v235
	v_cmp_lt_f32_e32 vcc, 4.0, v233
	s_cbranch_vccz .Lmla_nr_p1
	s_nop 15
	v_max_f32_e32 v234, 0, v233
	v_exp_f32_e64 v235, -v234
	v_add_f32_e32 v230, v230, v234
	v_sub_f32_e32 v34, v34, v234
	v_sub_f32_e32 v35, v35, v234
	v_sub_f32_e32 v36, v36, v234
	v_sub_f32_e32 v37, v37, v234
	v_sub_f32_e32 v38, v38, v234
	v_sub_f32_e32 v39, v39, v234
	v_sub_f32_e32 v40, v40, v234
	v_sub_f32_e32 v41, v41, v234
	v_sub_f32_e32 v42, v42, v234
	v_sub_f32_e32 v43, v43, v234
	v_sub_f32_e32 v44, v44, v234
	v_sub_f32_e32 v45, v45, v234
	v_sub_f32_e32 v46, v46, v234
	v_sub_f32_e32 v47, v47, v234
	v_sub_f32_e32 v48, v48, v234
	v_sub_f32_e32 v49, v49, v234
	v_sub_f32_e32 v50, v50, v234
	v_sub_f32_e32 v51, v51, v234
	v_sub_f32_e32 v52, v52, v234
	v_sub_f32_e32 v53, v53, v234
	v_sub_f32_e32 v54, v54, v234
	v_sub_f32_e32 v55, v55, v234
	v_sub_f32_e32 v56, v56, v234
	v_sub_f32_e32 v57, v57, v234
	v_sub_f32_e32 v58, v58, v234
	v_sub_f32_e32 v59, v59, v234
	v_sub_f32_e32 v60, v60, v234
	v_sub_f32_e32 v61, v61, v234
	v_sub_f32_e32 v62, v62, v234
	v_sub_f32_e32 v63, v63, v234
	v_sub_f32_e32 v64, v64, v234
	v_sub_f32_e32 v65, v65, v234
	v_mul_f32_e32 v231, v231, v235
	v_mul_f32_e32 v232, v232, v235
	v_mul_f32_e32 v2, v2, v235
	v_mul_f32_e32 v3, v3, v235
	v_mul_f32_e32 v4, v4, v235
	v_mul_f32_e32 v5, v5, v235
	v_mul_f32_e32 v6, v6, v235
	v_mul_f32_e32 v7, v7, v235
	v_mul_f32_e32 v8, v8, v235
	v_mul_f32_e32 v9, v9, v235
	v_mul_f32_e32 v10, v10, v235
	v_mul_f32_e32 v11, v11, v235
	v_mul_f32_e32 v12, v12, v235
	v_mul_f32_e32 v13, v13, v235
	v_mul_f32_e32 v14, v14, v235
	v_mul_f32_e32 v15, v15, v235
	v_mul_f32_e32 v16, v16, v235
	v_mul_f32_e32 v17, v17, v235
	v_mul_f32_e32 v18, v18, v235
	v_mul_f32_e32 v19, v19, v235
	v_mul_f32_e32 v20, v20, v235
	v_mul_f32_e32 v21, v21, v235
	v_mul_f32_e32 v22, v22, v235
	v_mul_f32_e32 v23, v23, v235
	v_mul_f32_e32 v24, v24, v235
	v_mul_f32_e32 v25, v25, v235
	v_mul_f32_e32 v26, v26, v235
	v_mul_f32_e32 v27, v27, v235
	v_mul_f32_e32 v28, v28, v235
	v_mul_f32_e32 v29, v29, v235
	v_mul_f32_e32 v30, v30, v235
	v_mul_f32_e32 v31, v31, v235
	v_mul_f32_e32 v32, v32, v235
	v_mul_f32_e32 v33, v33, v235
	v_sub_f32_e32 v122, 0, v230
	v_mov_b32_e32 v123, v122
	v_mov_b32_e32 v124, v122
	v_mov_b32_e32 v125, v122
	v_mov_b32_e32 v126, v122
	v_mov_b32_e32 v127, v122
	v_mov_b32_e32 v128, v122
	v_mov_b32_e32 v129, v122
	v_mov_b32_e32 v130, v122
	v_mov_b32_e32 v131, v122
	v_mov_b32_e32 v132, v122
	v_mov_b32_e32 v133, v122
	v_mov_b32_e32 v134, v122
	v_mov_b32_e32 v135, v122
	v_mov_b32_e32 v136, v122
	v_mov_b32_e32 v137, v122
.Lmla_nr_p1:
	ds_read_b128 v[138:141], v220 offset:39936
	ds_read_b128 v[142:145], v220 offset:46592
	ds_read_b128 v[146:149], v220 offset:39968
	ds_read_b128 v[150:153], v220 offset:46624
	ds_read_b128 v[154:157], v220 offset:40000
	ds_read_b128 v[158:161], v220 offset:46656
	s_waitcnt lgkmcnt(6)
	s_barrier
	v_exp_f32_e32 v34, v34
	v_exp_f32_e32 v35, v35
	v_exp_f32_e32 v36, v36
	v_exp_f32_e32 v37, v37
	s_waitcnt lgkmcnt(4)
	v_mfma_f32_32x32x16_bf16 v[66:81], v[138:141], v[98:101], v[122:137]
	ds_read_b128 v[138:141], v220 offset:40032
	v_add_f32_e32 v231, v231, v34
	v_add_f32_e32 v232, v232, v35
	v_exp_f32_e32 v38, v38
	v_exp_f32_e32 v39, v39
	v_mfma_f32_32x32x16_bf16 v[82:97], v[142:145], v[98:101], v[122:137]
	ds_read_b128 v[142:145], v220 offset:46688
	v_add_f32_e32 v231, v231, v36
	v_add_f32_e32 v232, v232, v37
	v_exp_f32_e32 v40, v40
	v_exp_f32_e32 v41, v41
	s_waitcnt lgkmcnt(4)
	v_mfma_f32_32x32x16_bf16 v[66:81], v[146:149], v[102:105], v[66:81]
	ds_read_b128 v[146:149], v220 offset:40064
	global_load_dwordx4 v[200:203], v226, s[4:5]
	global_load_dwordx4 v[204:207], v227, s[4:5]
	global_load_dwordx4 v[208:211], v228, s[4:5]
	s_add_u32 s4, s4, 0x6000
	s_addc_u32 s5, s5, 0
	global_load_dwordx4 v[212:215], v229, s[10:11]
	s_add_u32 s10, s10, 0x80
	s_addc_u32 s11, s11, 0
	v_add_f32_e32 v231, v231, v38
	v_add_f32_e32 v232, v232, v39
	v_add_f32_e32 v231, v231, v40
	v_add_f32_e32 v232, v232, v41
	v_cvt_pk_bf16_f32 v34, v34, v35
	v_cvt_pk_bf16_f32 v35, v36, v37
	v_mfma_f32_32x32x16_bf16 v[82:97], v[150:153], v[102:105], v[82:97]
	ds_read_b128 v[150:153], v220 offset:46720
	v_cvt_pk_bf16_f32 v36, v38, v39
	v_cvt_pk_bf16_f32 v37, v40, v41
	v_exp_f32_e32 v42, v42
	v_exp_f32_e32 v43, v43
	s_waitcnt lgkmcnt(4)
	v_mfma_f32_32x32x16_bf16 v[66:81], v[154:157], v[106:109], v[66:81]
	ds_read_b128 v[154:157], v220 offset:40096
	v_exp_f32_e32 v44, v44
	v_exp_f32_e32 v45, v45
	v_add_f32_e32 v231, v231, v42
	v_add_f32_e32 v232, v232, v43
	v_mfma_f32_32x32x16_bf16 v[82:97], v[158:161], v[106:109], v[82:97]
	ds_read_b128 v[158:161], v220 offset:46752
	v_exp_f32_e32 v46, v46
	v_exp_f32_e32 v47, v47
	v_add_f32_e32 v231, v231, v44
	v_add_f32_e32 v232, v232, v45
	v_exp_f32_e32 v48, v48
	s_waitcnt lgkmcnt(4)
	v_mfma_f32_32x32x16_bf16 v[66:81], v[138:141], v[110:113], v[66:81]
	ds_read_b64 v[162:163], v221 offset:17408
	ds_read_b64 v[164:165], v221 offset:17424
	v_exp_f32_e32 v49, v49
	v_add_f32_e32 v231, v231, v46
	v_add_f32_e32 v232, v232, v47
	v_add_f32_e32 v231, v231, v48
	v_mfma_f32_32x32x16_bf16 v[82:97], v[142:145], v[110:113], v[82:97]
	ds_read_b64 v[166:167], v221 offset:21760
	ds_read_b64 v[168:169], v221 offset:21776
	v_add_f32_e32 v232, v232, v49
	v_cvt_pk_bf16_f32 v42, v42, v43
	v_cvt_pk_bf16_f32 v43, v44, v45
	v_cvt_pk_bf16_f32 v44, v46, v47
	v_cvt_pk_bf16_f32 v45, v48, v49
	v_exp_f32_e32 v50, v50
	s_waitcnt lgkmcnt(6)
	v_mfma_f32_32x32x16_bf16 v[66:81], v[146:149], v[114:117], v[66:81]
	ds_read_b64 v[170:171], v221 offset:17440
	ds_read_b64 v[172:173], v221 offset:17456
	v_exp_f32_e32 v51, v51
	v_exp_f32_e32 v52, v52
	v_exp_f32_e32 v53, v53
	v_mfma_f32_32x32x16_bf16 v[82:97], v[150:153], v[114:117], v[82:97]
	ds_read_b64 v[174:175], v221 offset:21792
	ds_read_b64 v[176:177], v221 offset:21808
	v_add_f32_e32 v231, v231, v50
	v_add_f32_e32 v232, v232, v51
	v_exp_f32_e32 v54, v54
	v_exp_f32_e32 v55, v55
	s_waitcnt lgkmcnt(8)
	v_mfma_f32_32x32x16_bf16 v[66:81], v[154:157], v[118:121], v[66:81]
	ds_read_b64 v[180:181], v221 offset:17472
	ds_read_b64 v[182:183], v221 offset:17488
	v_add_f32_e32 v231, v231, v52
	v_add_f32_e32 v232, v232, v53
	v_exp_f32_e32 v56, v56
	v_exp_f32_e32 v57, v57
	v_mfma_f32_32x32x16_bf16 v[82:97], v[158:161], v[118:121], v[82:97]
	ds_read_b64 v[184:185], v221 offset:21824
	ds_read_b64 v[186:187], v221 offset:21840
	v_add_f32_e32 v231, v231, v54
	v_add_f32_e32 v232, v232, v55
	v_add_f32_e32 v231, v231, v56
	v_add_f32_e32 v232, v232, v57
	v_cvt_pk_bf16_f32 v50, v50, v51
	v_cvt_pk_bf16_f32 v51, v52, v53
	v_cvt_pk_bf16_f32 v52, v54, v55
	s_waitcnt lgkmcnt(8)
	v_mfma_f32_32x32x16_bf16 v[2:17], v[162:165], v[34:37], v[2:17]
	ds_read_b64 v[188:189], v221 offset:17504
	ds_read_b64 v[190:191], v221 offset:17520
	v_cvt_pk_bf16_f32 v53, v56, v57
	v_exp_f32_e32 v58, v58
	v_exp_f32_e32 v59, v59
	v_exp_f32_e32 v60, v60
	v_mfma_f32_32x32x16_bf16 v[18:33], v[166:169], v[34:37], v[18:33]
	ds_read_b64 v[192:193], v221 offset:21856
	ds_read_b64 v[194:195], v221 offset:21872
	v_exp_f32_e32 v61, v61
	v_add_f32_e32 v231, v231, v58
	v_add_f32_e32 v232, v232, v59
	v_exp_f32_e32 v62, v62
	s_waitcnt lgkmcnt(8)
	v_mfma_f32_32x32x16_bf16 v[2:17], v[170:173], v[42:45], v[2:17]
	v_exp_f32_e32 v63, v63
	v_add_f32_e32 v231, v231, v60
	v_add_f32_e32 v232, v232, v61
	v_exp_f32_e32 v64, v64
	v_mfma_f32_32x32x16_bf16 v[18:33], v[174:177], v[42:45], v[18:33]
	s_waitcnt vmcnt(4)
	ds_write_b64 v225, v[216:217] offset:0
	ds_write_b64 v225, v[218:219] offset:8
	v_exp_f32_e32 v65, v65
	v_add_f32_e32 v231, v231, v62
	v_add_f32_e32 v232, v232, v63
	v_add_f32_e32 v231, v231, v64
	v_add_f32_e32 v232, v232, v65
	s_waitcnt lgkmcnt(6)
	v_mfma_f32_32x32x16_bf16 v[2:17], v[180:183], v[50:53], v[2:17]
	v_cvt_pk_bf16_f32 v58, v58, v59
	v_cvt_pk_bf16_f32 v59, v60, v61
	v_cvt_pk_bf16_f32 v60, v62, v63
	v_cvt_pk_bf16_f32 v61, v64, v65
	v_max3_f32 v234, v66, v67, v68
	v_max3_f32 v235, v82, v83, v84
	v_mfma_f32_32x32x16_bf16 v[18:33], v[184:187], v[50:53], v[18:33]
	v_max3_f32 v234, v234, v69, v70
	v_max3_f32 v235, v235, v85, v86
	v_max3_f32 v234, v234, v71, v72
	v_max3_f32 v235, v235, v87, v88
	v_max3_f32 v234, v234, v73, v74
	v_max3_f32 v235, v235, v89, v90
	v_max3_f32 v234, v234, v75, v76
	s_waitcnt lgkmcnt(2)
	v_mfma_f32_32x32x16_bf16 v[2:17], v[188:191], v[58:61], v[2:17]
	v_max3_f32 v235, v235, v91, v92
	v_max3_f32 v234, v234, v77, v78
	v_max3_f32 v235, v235, v93, v94
	v_max3_f32 v234, v234, v79, v80
	v_max3_f32 v235, v235, v95, v96
	v_max3_f32 v234, v234, v81, v97
	v_mfma_f32_32x32x16_bf16 v[18:33], v[192:195], v[58:61], v[18:33]
	v_max_f32_e32 v234, v234, v235
	v_mov_b32_e32 v235, v234
	s_nop 1
	v_permlane32_swap_b32_e32 v234, v235
	v_max_f32_e32 v233, v234, v235
	v_cmp_lt_f32_e32 vcc, 4.0, v233
	s_cbranch_vccz .Lmla_nr_p2
	s_nop 15
	v_max_f32_e32 v234, 0, v233
	v_exp_f32_e64 v235, -v234
	v_add_f32_e32 v230, v230, v234
	v_sub_f32_e32 v66, v66, v234
	v_sub_f32_e32 v67, v67, v234
	v_sub_f32_e32 v68, v68, v234
	v_sub_f32_e32 v69, v69, v234
	v_sub_f32_e32 v70, v70, v234
	v_sub_f32_e32 v71, v71, v234
	v_sub_f32_e32 v72, v72, v234
	v_sub_f32_e32 v73, v73, v234
	v_sub_f32_e32 v74, v74, v234
	v_sub_f32_e32 v75, v75, v234
	v_sub_f32_e32 v76, v76, v234
	v_sub_f32_e32 v77, v77, v234
	v_sub_f32_e32 v78, v78, v234
	v_sub_f32_e32 v79, v79, v234
	v_sub_f32_e32 v80, v80, v234
	v_sub_f32_e32 v81, v81, v234
	v_sub_f32_e32 v82, v82, v234
	v_sub_f32_e32 v83, v83, v234
	v_sub_f32_e32 v84, v84, v234
	v_sub_f32_e32 v85, v85, v234
	v_sub_f32_e32 v86, v86, v234
	v_sub_f32_e32 v87, v87, v234
	v_sub_f32_e32 v88, v88, v234
	v_sub_f32_e32 v89, v89, v234
	v_sub_f32_e32 v90, v90, v234
	v_sub_f32_e32 v91, v91, v234
	v_sub_f32_e32 v92, v92, v234
	v_sub_f32_e32 v93, v93, v234
	v_sub_f32_e32 v94, v94, v234
	v_sub_f32_e32 v95, v95, v234
	v_sub_f32_e32 v96, v96, v234
	v_sub_f32_e32 v97, v97, v234
	v_mul_f32_e32 v231, v231, v235
	v_mul_f32_e32 v232, v232, v235
	v_mul_f32_e32 v2, v2, v235
	v_mul_f32_e32 v3, v3, v235
	v_mul_f32_e32 v4, v4, v235
	v_mul_f32_e32 v5, v5, v235
	v_mul_f32_e32 v6, v6, v235
	v_mul_f32_e32 v7, v7, v235
	v_mul_f32_e32 v8, v8, v235
	v_mul_f32_e32 v9, v9, v235
	v_mul_f32_e32 v10, v10, v235
	v_mul_f32_e32 v11, v11, v235
	v_mul_f32_e32 v12, v12, v235
	v_mul_f32_e32 v13, v13, v235
	v_mul_f32_e32 v14, v14, v235
	v_mul_f32_e32 v15, v15, v235
	v_mul_f32_e32 v16, v16, v235
	v_mul_f32_e32 v17, v17, v235
	v_mul_f32_e32 v18, v18, v235
	v_mul_f32_e32 v19, v19, v235
	v_mul_f32_e32 v20, v20, v235
	v_mul_f32_e32 v21, v21, v235
	v_mul_f32_e32 v22, v22, v235
	v_mul_f32_e32 v23, v23, v235
	v_mul_f32_e32 v24, v24, v235
	v_mul_f32_e32 v25, v25, v235
	v_mul_f32_e32 v26, v26, v235
	v_mul_f32_e32 v27, v27, v235
	v_mul_f32_e32 v28, v28, v235
	v_mul_f32_e32 v29, v29, v235
	v_mul_f32_e32 v30, v30, v235
	v_mul_f32_e32 v31, v31, v235
	v_mul_f32_e32 v32, v32, v235
	v_mul_f32_e32 v33, v33, v235
	v_sub_f32_e32 v122, 0, v230
	v_mov_b32_e32 v123, v122
	v_mov_b32_e32 v124, v122
	v_mov_b32_e32 v125, v122
	v_mov_b32_e32 v126, v122
	v_mov_b32_e32 v127, v122
	v_mov_b32_e32 v128, v122
	v_mov_b32_e32 v129, v122
	v_mov_b32_e32 v130, v122
	v_mov_b32_e32 v131, v122
	v_mov_b32_e32 v132, v122
	v_mov_b32_e32 v133, v122
	v_mov_b32_e32 v134, v122
	v_mov_b32_e32 v135, v122
	v_mov_b32_e32 v136, v122
	v_mov_b32_e32 v137, v122
.Lmla_nr_p2:
	ds_read_b128 v[138:141], v220 offset:0
	ds_read_b128 v[142:145], v220 offset:6656
	ds_read_b128 v[146:149], v220 offset:32
	ds_read_b128 v[150:153], v220 offset:6688
	ds_read_b128 v[154:157], v220 offset:64
	ds_read_b128 v[158:161], v220 offset:6720
	s_waitcnt lgkmcnt(6)
	s_barrier
	v_exp_f32_e32 v66, v66
	v_exp_f32_e32 v67, v67
	v_exp_f32_e32 v68, v68
	v_exp_f32_e32 v69, v69
	s_waitcnt lgkmcnt(4)
	v_mfma_f32_32x32x16_bf16 v[34:49], v[138:141], v[98:101], v[122:137]
	ds_read_b128 v[138:141], v220 offset:96
	v_add_f32_e32 v231, v231, v66
	v_add_f32_e32 v232, v232, v67
	v_exp_f32_e32 v70, v70
	v_exp_f32_e32 v71, v71
	v_mfma_f32_32x32x16_bf16 v[50:65], v[142:145], v[98:101], v[122:137]
	ds_read_b128 v[142:145], v220 offset:6752
	v_add_f32_e32 v231, v231, v68
	v_add_f32_e32 v232, v232, v69
	v_exp_f32_e32 v72, v72
	v_exp_f32_e32 v73, v73
	s_waitcnt lgkmcnt(4)
	v_mfma_f32_32x32x16_bf16 v[34:49], v[146:149], v[102:105], v[34:49]
	ds_read_b128 v[146:149], v220 offset:128
	global_load_dwordx4 v[216:219], v229, s[10:11]
	s_add_u32 s10, s10, 0x80
	s_addc_u32 s11, s11, 0
	v_add_f32_e32 v231, v231, v70
	v_add_f32_e32 v232, v232, v71
	v_add_f32_e32 v231, v231, v72
	v_add_f32_e32 v232, v232, v73
	v_cvt_pk_bf16_f32 v66, v66, v67
	v_cvt_pk_bf16_f32 v67, v68, v69
	v_mfma_f32_32x32x16_bf16 v[50:65], v[150:153], v[102:105], v[50:65]
	ds_read_b128 v[150:153], v220 offset:6784
	v_cvt_pk_bf16_f32 v68, v70, v71
	v_cvt_pk_bf16_f32 v69, v72, v73
	v_exp_f32_e32 v74, v74
	v_exp_f32_e32 v75, v75
	s_waitcnt lgkmcnt(4)
	v_mfma_f32_32x32x16_bf16 v[34:49], v[154:157], v[106:109], v[34:49]
	ds_read_b128 v[154:157], v220 offset:160
	v_exp_f32_e32 v76, v76
	v_exp_f32_e32 v77, v77
	v_add_f32_e32 v231, v231, v74
	v_add_f32_e32 v232, v232, v75
	v_mfma_f32_32x32x16_bf16 v[50:65], v[158:161], v[106:109], v[50:65]
	ds_read_b128 v[158:161], v220 offset:6816
	v_exp_f32_e32 v78, v78
	v_exp_f32_e32 v79, v79
	v_add_f32_e32 v231, v231, v76
	v_add_f32_e32 v232, v232, v77
	v_exp_f32_e32 v80, v80
	s_waitcnt lgkmcnt(4)
	v_mfma_f32_32x32x16_bf16 v[34:49], v[138:141], v[110:113], v[34:49]
	ds_read_b64 v[162:163], v221 offset:26112
	ds_read_b64 v[164:165], v221 offset:26128
	v_exp_f32_e32 v81, v81
	v_add_f32_e32 v231, v231, v78
	v_add_f32_e32 v232, v232, v79
	v_add_f32_e32 v231, v231, v80
	v_mfma_f32_32x32x16_bf16 v[50:65], v[142:145], v[110:113], v[50:65]
	ds_read_b64 v[166:167], v221 offset:30464
	ds_read_b64 v[168:169], v221 offset:30480
	v_add_f32_e32 v232, v232, v81
	v_cvt_pk_bf16_f32 v74, v74, v75
	v_cvt_pk_bf16_f32 v75, v76, v77
	v_cvt_pk_bf16_f32 v76, v78, v79
	v_cvt_pk_bf16_f32 v77, v80, v81
	v_exp_f32_e32 v82, v82
	s_waitcnt lgkmcnt(6)
	v_mfma_f32_32x32x16_bf16 v[34:49], v[146:149], v[114:117], v[34:49]
	ds_read_b64 v[170:171], v221 offset:26144
	ds_read_b64 v[172:173], v221 offset:26160
	v_exp_f32_e32 v83, v83
	v_exp_f32_e32 v84, v84
	v_exp_f32_e32 v85, v85
	v_mfma_f32_32x32x16_bf16 v[50:65], v[150:153], v[114:117], v[50:65]
	ds_read_b64 v[174:175], v221 offset:30496
	ds_read_b64 v[176:177], v221 offset:30512
	v_add_f32_e32 v231, v231, v82
	v_add_f32_e32 v232, v232, v83
	v_exp_f32_e32 v86, v86
	v_exp_f32_e32 v87, v87
	s_waitcnt lgkmcnt(8)
	v_mfma_f32_32x32x16_bf16 v[34:49], v[154:157], v[118:121], v[34:49]
	ds_read_b64 v[180:181], v221 offset:26176
	ds_read_b64 v[182:183], v221 offset:26192
	v_add_f32_e32 v231, v231, v84
	v_add_f32_e32 v232, v232, v85
	v_exp_f32_e32 v88, v88
	v_exp_f32_e32 v89, v89
	v_mfma_f32_32x32x16_bf16 v[50:65], v[158:161], v[118:121], v[50:65]
	ds_read_b64 v[184:185], v221 offset:30528
	ds_read_b64 v[186:187], v221 offset:30544
	v_add_f32_e32 v231, v231, v86
	v_add_f32_e32 v232, v232, v87
	v_add_f32_e32 v231, v231, v88
	v_add_f32_e32 v232, v232, v89
	v_cvt_pk_bf16_f32 v82, v82, v83
	v_cvt_pk_bf16_f32 v83, v84, v85
	v_cvt_pk_bf16_f32 v84, v86, v87
	s_waitcnt lgkmcnt(8)
	v_mfma_f32_32x32x16_bf16 v[2:17], v[162:165], v[66:69], v[2:17]
	ds_read_b64 v[188:189], v221 offset:26208
	ds_read_b64 v[190:191], v221 offset:26224
	v_cvt_pk_bf16_f32 v85, v88, v89
	v_exp_f32_e32 v90, v90
	v_exp_f32_e32 v91, v91
	v_exp_f32_e32 v92, v92
	v_mfma_f32_32x32x16_bf16 v[18:33], v[166:169], v[66:69], v[18:33]
	ds_read_b64 v[192:193], v221 offset:30560
	ds_read_b64 v[194:195], v221 offset:30576
	v_exp_f32_e32 v93, v93
	v_add_f32_e32 v231, v231, v90
	v_add_f32_e32 v232, v232, v91
	v_exp_f32_e32 v94, v94
	s_waitcnt lgkmcnt(8)
	v_mfma_f32_32x32x16_bf16 v[2:17], v[170:173], v[74:77], v[2:17]
	v_exp_f32_e32 v95, v95
	v_add_f32_e32 v231, v231, v92
	v_add_f32_e32 v232, v232, v93
	v_exp_f32_e32 v96, v96
	v_mfma_f32_32x32x16_bf16 v[18:33], v[174:177], v[74:77], v[18:33]
	s_waitcnt vmcnt(1)
	ds_write_b128 v222, v[200:203] offset:26624
	ds_write_b128 v223, v[204:207] offset:26624
	ds_write_b128 v224, v[208:211] offset:26624
	ds_write_b64 v225, v[212:213] offset:8704
	ds_write_b64 v225, v[214:215] offset:8712
	v_exp_f32_e32 v97, v97
	v_add_f32_e32 v231, v231, v94
	v_add_f32_e32 v232, v232, v95
	v_add_f32_e32 v231, v231, v96
	v_add_f32_e32 v232, v232, v97
	s_waitcnt lgkmcnt(9)
	v_mfma_f32_32x32x16_bf16 v[2:17], v[180:183], v[82:85], v[2:17]
	v_cvt_pk_bf16_f32 v90, v90, v91
	v_cvt_pk_bf16_f32 v91, v92, v93
	v_cvt_pk_bf16_f32 v92, v94, v95
	v_cvt_pk_bf16_f32 v93, v96, v97
	v_max3_f32 v234, v34, v35, v36
	v_max3_f32 v235, v50, v51, v52
	v_mfma_f32_32x32x16_bf16 v[18:33], v[184:187], v[82:85], v[18:33]
	v_max3_f32 v234, v234, v37, v38
	v_max3_f32 v235, v235, v53, v54
	v_max3_f32 v234, v234, v39, v40
	v_max3_f32 v235, v235, v55, v56
	v_max3_f32 v234, v234, v41, v42
	v_max3_f32 v235, v235, v57, v58
	v_max3_f32 v234, v234, v43, v44
	s_waitcnt lgkmcnt(5)
	v_mfma_f32_32x32x16_bf16 v[2:17], v[188:191], v[90:93], v[2:17]
	v_max3_f32 v235, v235, v59, v60
	v_max3_f32 v234, v234, v45, v46
	v_max3_f32 v235, v235, v61, v62
	v_max3_f32 v234, v234, v47, v48
	v_max3_f32 v235, v235, v63, v64
	v_max3_f32 v234, v234, v49, v65
	v_mfma_f32_32x32x16_bf16 v[18:33], v[192:195], v[90:93], v[18:33]
	v_max_f32_e32 v234, v234, v235
	v_mov_b32_e32 v235, v234
	s_nop 1
	v_permlane32_swap_b32_e32 v234, v235
	v_max_f32_e32 v233, v234, v235
	v_cmp_lt_f32_e32 vcc, 4.0, v233
	s_cbranch_vccz .Lmla_nr_p3
	s_nop 15
	v_max_f32_e32 v234, 0, v233
	v_exp_f32_e64 v235, -v234
	v_add_f32_e32 v230, v230, v234
	v_sub_f32_e32 v34, v34, v234
	v_sub_f32_e32 v35, v35, v234
	v_sub_f32_e32 v36, v36, v234
	v_sub_f32_e32 v37, v37, v234
	v_sub_f32_e32 v38, v38, v234
	v_sub_f32_e32 v39, v39, v234
	v_sub_f32_e32 v40, v40, v234
	v_sub_f32_e32 v41, v41, v234
	v_sub_f32_e32 v42, v42, v234
	v_sub_f32_e32 v43, v43, v234
	v_sub_f32_e32 v44, v44, v234
	v_sub_f32_e32 v45, v45, v234
	v_sub_f32_e32 v46, v46, v234
	v_sub_f32_e32 v47, v47, v234
	v_sub_f32_e32 v48, v48, v234
	v_sub_f32_e32 v49, v49, v234
	v_sub_f32_e32 v50, v50, v234
	v_sub_f32_e32 v51, v51, v234
	v_sub_f32_e32 v52, v52, v234
	v_sub_f32_e32 v53, v53, v234
	v_sub_f32_e32 v54, v54, v234
	v_sub_f32_e32 v55, v55, v234
	v_sub_f32_e32 v56, v56, v234
	v_sub_f32_e32 v57, v57, v234
	v_sub_f32_e32 v58, v58, v234
	v_sub_f32_e32 v59, v59, v234
	v_sub_f32_e32 v60, v60, v234
	v_sub_f32_e32 v61, v61, v234
	v_sub_f32_e32 v62, v62, v234
	v_sub_f32_e32 v63, v63, v234
	v_sub_f32_e32 v64, v64, v234
	v_sub_f32_e32 v65, v65, v234
	v_mul_f32_e32 v231, v231, v235
	v_mul_f32_e32 v232, v232, v235
	v_mul_f32_e32 v2, v2, v235
	v_mul_f32_e32 v3, v3, v235
	v_mul_f32_e32 v4, v4, v235
	v_mul_f32_e32 v5, v5, v235
	v_mul_f32_e32 v6, v6, v235
	v_mul_f32_e32 v7, v7, v235
	v_mul_f32_e32 v8, v8, v235
	v_mul_f32_e32 v9, v9, v235
	v_mul_f32_e32 v10, v10, v235
	v_mul_f32_e32 v11, v11, v235
	v_mul_f32_e32 v12, v12, v235
	v_mul_f32_e32 v13, v13, v235
	v_mul_f32_e32 v14, v14, v235
	v_mul_f32_e32 v15, v15, v235
	v_mul_f32_e32 v16, v16, v235
	v_mul_f32_e32 v17, v17, v235
	v_mul_f32_e32 v18, v18, v235
	v_mul_f32_e32 v19, v19, v235
	v_mul_f32_e32 v20, v20, v235
	v_mul_f32_e32 v21, v21, v235
	v_mul_f32_e32 v22, v22, v235
	v_mul_f32_e32 v23, v23, v235
	v_mul_f32_e32 v24, v24, v235
	v_mul_f32_e32 v25, v25, v235
	v_mul_f32_e32 v26, v26, v235
	v_mul_f32_e32 v27, v27, v235
	v_mul_f32_e32 v28, v28, v235
	v_mul_f32_e32 v29, v29, v235
	v_mul_f32_e32 v30, v30, v235
	v_mul_f32_e32 v31, v31, v235
	v_mul_f32_e32 v32, v32, v235
	v_mul_f32_e32 v33, v33, v235
	v_sub_f32_e32 v122, 0, v230
	v_mov_b32_e32 v123, v122
	v_mov_b32_e32 v124, v122
	v_mov_b32_e32 v125, v122
	v_mov_b32_e32 v126, v122
	v_mov_b32_e32 v127, v122
	v_mov_b32_e32 v128, v122
	v_mov_b32_e32 v129, v122
	v_mov_b32_e32 v130, v122
	v_mov_b32_e32 v131, v122
	v_mov_b32_e32 v132, v122
	v_mov_b32_e32 v133, v122
	v_mov_b32_e32 v134, v122
	v_mov_b32_e32 v135, v122
	v_mov_b32_e32 v136, v122
	v_mov_b32_e32 v137, v122
.Lmla_nr_p3:
	ds_read_b128 v[138:141], v220 offset:13312
	ds_read_b128 v[142:145], v220 offset:19968
	ds_read_b128 v[146:149], v220 offset:13344
	ds_read_b128 v[150:153], v220 offset:20000
	ds_read_b128 v[154:157], v220 offset:13376
	ds_read_b128 v[158:161], v220 offset:20032
	s_waitcnt lgkmcnt(6)
	s_barrier
	s_add_i32 s16, s16, -1
	s_cmp_lg_u32 s16, 0
	s_cbranch_scc1 .Lmla_loop
	v_exp_f32_e32 v34, v34
	v_exp_f32_e32 v35, v35
	v_exp_f32_e32 v36, v36
	v_exp_f32_e32 v37, v37
	s_waitcnt lgkmcnt(4)
	v_mfma_f32_32x32x16_bf16 v[66:81], v[138:141], v[98:101], v[122:137]
	ds_read_b128 v[138:141], v220 offset:13408
	v_add_f32_e32 v231, v231, v34
	v_add_f32_e32 v232, v232, v35
	v_exp_f32_e32 v38, v38
	v_exp_f32_e32 v39, v39
	v_mfma_f32_32x32x16_bf16 v[82:97], v[142:145], v[98:101], v[122:137]
	ds_read_b128 v[142:145], v220 offset:20064
	v_add_f32_e32 v231, v231, v36
	v_add_f32_e32 v232, v232, v37
	v_exp_f32_e32 v40, v40
	v_exp_f32_e32 v41, v41
	s_waitcnt lgkmcnt(4)
	v_mfma_f32_32x32x16_bf16 v[66:81], v[146:149], v[102:105], v[66:81]
	ds_read_b128 v[146:149], v220 offset:13440
	global_load_dwordx4 v[212:215], v229, s[10:11]
	s_add_u32 s10, s10, 0x80
	s_addc_u32 s11, s11, 0
	v_add_f32_e32 v231, v231, v38
	v_add_f32_e32 v232, v232, v39
	v_add_f32_e32 v231, v231, v40
	v_add_f32_e32 v232, v232, v41
	v_cvt_pk_bf16_f32 v34, v34, v35
	v_cvt_pk_bf16_f32 v35, v36, v37
	v_mfma_f32_32x32x16_bf16 v[82:97], v[150:153], v[102:105], v[82:97]
	ds_read_b128 v[150:153], v220 offset:20096
	v_cvt_pk_bf16_f32 v36, v38, v39
	v_cvt_pk_bf16_f32 v37, v40, v41
	v_exp_f32_e32 v42, v42
	v_exp_f32_e32 v43, v43
	s_waitcnt lgkmcnt(4)
	v_mfma_f32_32x32x16_bf16 v[66:81], v[154:157], v[106:109], v[66:81]
	ds_read_b128 v[154:157], v220 offset:13472
	v_exp_f32_e32 v44, v44
	v_exp_f32_e32 v45, v45
	v_add_f32_e32 v231, v231, v42
	v_add_f32_e32 v232, v232, v43
	v_mfma_f32_32x32x16_bf16 v[82:97], v[158:161], v[106:109], v[82:97]
	ds_read_b128 v[158:161], v220 offset:20128
	v_exp_f32_e32 v46, v46
	v_exp_f32_e32 v47, v47
	v_add_f32_e32 v231, v231, v44
	v_add_f32_e32 v232, v232, v45
	v_exp_f32_e32 v48, v48
	s_waitcnt lgkmcnt(4)
	v_mfma_f32_32x32x16_bf16 v[66:81], v[138:141], v[110:113], v[66:81]
	ds_read_b64 v[162:163], v221 offset:0
	ds_read_b64 v[164:165], v221 offset:16
	v_exp_f32_e32 v49, v49
	v_add_f32_e32 v231, v231, v46
	v_add_f32_e32 v232, v232, v47
	v_add_f32_e32 v231, v231, v48
	v_mfma_f32_32x32x16_bf16 v[82:97], v[142:145], v[110:113], v[82:97]
	ds_read_b64 v[166:167], v221 offset:4352
	ds_read_b64 v[168:169], v221 offset:4368
	v_add_f32_e32 v232, v232, v49
	v_cvt_pk_bf16_f32 v42, v42, v43
	v_cvt_pk_bf16_f32 v43, v44, v45
	v_cvt_pk_bf16_f32 v44, v46, v47
	v_cvt_pk_bf16_f32 v45, v48, v49
	v_exp_f32_e32 v50, v50
	s_waitcnt lgkmcnt(6)
	v_mfma_f32_32x32x16_bf16 v[66:81], v[146:149], v[114:117], v[66:81]
	ds_read_b64 v[170:171], v221 offset:32
	ds_read_b64 v[172:173], v221 offset:48
	v_exp_f32_e32 v51, v51
	v_exp_f32_e32 v52, v52
	v_exp_f32_e32 v53, v53
	v_mfma_f32_32x32x16_bf16 v[82:97], v[150:153], v[114:117], v[82:97]
	ds_read_b64 v[174:175], v221 offset:4384
	ds_read_b64 v[176:177], v221 offset:4400
	v_add_f32_e32 v231, v231, v50
	v_add_f32_e32 v232, v232, v51
	v_exp_f32_e32 v54, v54
	v_exp_f32_e32 v55, v55
	s_waitcnt lgkmcnt(8)
	v_mfma_f32_32x32x16_bf16 v[66:81], v[154:157], v[118:121], v[66:81]
	ds_read_b64 v[180:181], v221 offset:64
	ds_read_b64 v[182:183], v221 offset:80
	v_add_f32_e32 v231, v231, v52
	v_add_f32_e32 v232, v232, v53
	v_exp_f32_e32 v56, v56
	v_exp_f32_e32 v57, v57
	v_mfma_f32_32x32x16_bf16 v[82:97], v[158:161], v[118:121], v[82:97]
	ds_read_b64 v[184:185], v221 offset:4416
	ds_read_b64 v[186:187], v221 offset:4432
	v_add_f32_e32 v231, v231, v54
	v_add_f32_e32 v232, v232, v55
	v_add_f32_e32 v231, v231, v56
	v_add_f32_e32 v232, v232, v57
	v_cvt_pk_bf16_f32 v50, v50, v51
	v_cvt_pk_bf16_f32 v51, v52, v53
	v_cvt_pk_bf16_f32 v52, v54, v55
	s_waitcnt lgkmcnt(8)
	v_mfma_f32_32x32x16_bf16 v[2:17], v[162:165], v[34:37], v[2:17]
	ds_read_b64 v[188:189], v221 offset:96
	ds_read_b64 v[190:191], v221 offset:112
	v_cvt_pk_bf16_f32 v53, v56, v57
	v_exp_f32_e32 v58, v58
	v_exp_f32_e32 v59, v59
	v_exp_f32_e32 v60, v60
	v_mfma_f32_32x32x16_bf16 v[18:33], v[166:169], v[34:37], v[18:33]
	ds_read_b64 v[192:193], v221 offset:4448
	ds_read_b64 v[194:195], v221 offset:4464
	v_exp_f32_e32 v61, v61
	v_add_f32_e32 v231, v231, v58
	v_add_f32_e32 v232, v232, v59
	v_exp_f32_e32 v62, v62
	s_waitcnt lgkmcnt(8)
	v_mfma_f32_32x32x16_bf16 v[2:17], v[170:173], v[42:45], v[2:17]
	v_exp_f32_e32 v63, v63
	v_add_f32_e32 v231, v231, v60
	v_add_f32_e32 v232, v232, v61
	v_exp_f32_e32 v64, v64
	v_mfma_f32_32x32x16_bf16 v[18:33], v[174:177], v[42:45], v[18:33]
	s_waitcnt vmcnt(1)
	ds_write_b64 v225, v[216:217] offset:17408
	ds_write_b64 v225, v[218:219] offset:17416
	v_exp_f32_e32 v65, v65
	v_add_f32_e32 v231, v231, v62
	v_add_f32_e32 v232, v232, v63
	v_add_f32_e32 v231, v231, v64
	v_add_f32_e32 v232, v232, v65
	s_waitcnt lgkmcnt(6)
	v_mfma_f32_32x32x16_bf16 v[2:17], v[180:183], v[50:53], v[2:17]
	v_cvt_pk_bf16_f32 v58, v58, v59
	v_cvt_pk_bf16_f32 v59, v60, v61
	v_cvt_pk_bf16_f32 v60, v62, v63
	v_cvt_pk_bf16_f32 v61, v64, v65
	v_max3_f32 v234, v66, v67, v68
	v_max3_f32 v235, v82, v83, v84
	v_mfma_f32_32x32x16_bf16 v[18:33], v[184:187], v[50:53], v[18:33]
	v_max3_f32 v234, v234, v69, v70
	v_max3_f32 v235, v235, v85, v86
	v_max3_f32 v234, v234, v71, v72
	v_max3_f32 v235, v235, v87, v88
	v_max3_f32 v234, v234, v73, v74
	v_max3_f32 v235, v235, v89, v90
	v_max3_f32 v234, v234, v75, v76
	s_waitcnt lgkmcnt(2)
	v_mfma_f32_32x32x16_bf16 v[2:17], v[188:191], v[58:61], v[2:17]
	v_max3_f32 v235, v235, v91, v92
	v_max3_f32 v234, v234, v77, v78
	v_max3_f32 v235, v235, v93, v94
	v_max3_f32 v234, v234, v79, v80
	v_max3_f32 v235, v235, v95, v96
	v_max3_f32 v234, v234, v81, v97
	v_mfma_f32_32x32x16_bf16 v[18:33], v[192:195], v[58:61], v[18:33]
	v_max_f32_e32 v234, v234, v235
	v_mov_b32_e32 v235, v234
	s_nop 1
	v_permlane32_swap_b32_e32 v234, v235
	v_max_f32_e32 v233, v234, v235
	v_cmp_lt_f32_e32 vcc, 4.0, v233
	s_cbranch_vccz .Lmla_nr_t0
	s_nop 15
	v_max_f32_e32 v234, 0, v233
	v_exp_f32_e64 v235, -v234
	v_add_f32_e32 v230, v230, v234
	v_sub_f32_e32 v66, v66, v234
	v_sub_f32_e32 v67, v67, v234
	v_sub_f32_e32 v68, v68, v234
	v_sub_f32_e32 v69, v69, v234
	v_sub_f32_e32 v70, v70, v234
	v_sub_f32_e32 v71, v71, v234
	v_sub_f32_e32 v72, v72, v234
	v_sub_f32_e32 v73, v73, v234
	v_sub_f32_e32 v74, v74, v234
	v_sub_f32_e32 v75, v75, v234
	v_sub_f32_e32 v76, v76, v234
	v_sub_f32_e32 v77, v77, v234
	v_sub_f32_e32 v78, v78, v234
	v_sub_f32_e32 v79, v79, v234
	v_sub_f32_e32 v80, v80, v234
	v_sub_f32_e32 v81, v81, v234
	v_sub_f32_e32 v82, v82, v234
	v_sub_f32_e32 v83, v83, v234
	v_sub_f32_e32 v84, v84, v234
	v_sub_f32_e32 v85, v85, v234
	v_sub_f32_e32 v86, v86, v234
	v_sub_f32_e32 v87, v87, v234
	v_sub_f32_e32 v88, v88, v234
	v_sub_f32_e32 v89, v89, v234
	v_sub_f32_e32 v90, v90, v234
	v_sub_f32_e32 v91, v91, v234
	v_sub_f32_e32 v92, v92, v234
	v_sub_f32_e32 v93, v93, v234
	v_sub_f32_e32 v94, v94, v234
	v_sub_f32_e32 v95, v95, v234
	v_sub_f32_e32 v96, v96, v234
	v_sub_f32_e32 v97, v97, v234
	v_mul_f32_e32 v231, v231, v235
	v_mul_f32_e32 v232, v232, v235
	v_mul_f32_e32 v2, v2, v235
	v_mul_f32_e32 v3, v3, v235
	v_mul_f32_e32 v4, v4, v235
	v_mul_f32_e32 v5, v5, v235
	v_mul_f32_e32 v6, v6, v235
	v_mul_f32_e32 v7, v7, v235
	v_mul_f32_e32 v8, v8, v235
	v_mul_f32_e32 v9, v9, v235
	v_mul_f32_e32 v10, v10, v235
	v_mul_f32_e32 v11, v11, v235
	v_mul_f32_e32 v12, v12, v235
	v_mul_f32_e32 v13, v13, v235
	v_mul_f32_e32 v14, v14, v235
	v_mul_f32_e32 v15, v15, v235
	v_mul_f32_e32 v16, v16, v235
	v_mul_f32_e32 v17, v17, v235
	v_mul_f32_e32 v18, v18, v235
	v_mul_f32_e32 v19, v19, v235
	v_mul_f32_e32 v20, v20, v235
	v_mul_f32_e32 v21, v21, v235
	v_mul_f32_e32 v22, v22, v235
	v_mul_f32_e32 v23, v23, v235
	v_mul_f32_e32 v24, v24, v235
	v_mul_f32_e32 v25, v25, v235
	v_mul_f32_e32 v26, v26, v235
	v_mul_f32_e32 v27, v27, v235
	v_mul_f32_e32 v28, v28, v235
	v_mul_f32_e32 v29, v29, v235
	v_mul_f32_e32 v30, v30, v235
	v_mul_f32_e32 v31, v31, v235
	v_mul_f32_e32 v32, v32, v235
	v_mul_f32_e32 v33, v33, v235
	v_sub_f32_e32 v122, 0, v230
	v_mov_b32_e32 v123, v122
	v_mov_b32_e32 v124, v122
	v_mov_b32_e32 v125, v122
	v_mov_b32_e32 v126, v122
	v_mov_b32_e32 v127, v122
	v_mov_b32_e32 v128, v122
	v_mov_b32_e32 v129, v122
	v_mov_b32_e32 v130, v122
	v_mov_b32_e32 v131, v122
	v_mov_b32_e32 v132, v122
	v_mov_b32_e32 v133, v122
	v_mov_b32_e32 v134, v122
	v_mov_b32_e32 v135, v122
	v_mov_b32_e32 v136, v122
	v_mov_b32_e32 v137, v122
.Lmla_nr_t0:
	ds_read_b128 v[138:141], v220 offset:26624
	ds_read_b128 v[142:145], v220 offset:33280
	ds_read_b128 v[146:149], v220 offset:26656
	ds_read_b128 v[150:153], v220 offset:33312
	ds_read_b128 v[154:157], v220 offset:26688
	ds_read_b128 v[158:161], v220 offset:33344
	s_waitcnt lgkmcnt(6)
	s_barrier
	v_exp_f32_e32 v66, v66
	v_exp_f32_e32 v67, v67
	v_exp_f32_e32 v68, v68
	v_exp_f32_e32 v69, v69
	s_waitcnt lgkmcnt(4)
	v_mfma_f32_32x32x16_bf16 v[34:49], v[138:141], v[98:101], v[122:137]
	ds_read_b128 v[138:141], v220 offset:26720
	v_add_f32_e32 v231, v231, v66
	v_add_f32_e32 v232, v232, v67
	v_exp_f32_e32 v70, v70
	v_exp_f32_e32 v71, v71
	v_mfma_f32_32x32x16_bf16 v[50:65], v[142:145], v[98:101], v[122:137]
	ds_read_b128 v[142:145], v220 offset:33376
	v_add_f32_e32 v231, v231, v68
	v_add_f32_e32 v232, v232, v69
	v_exp_f32_e32 v72, v72
	v_exp_f32_e32 v73, v73
	s_waitcnt lgkmcnt(4)
	v_mfma_f32_32x32x16_bf16 v[34:49], v[146:149], v[102:105], v[34:49]
	ds_read_b128 v[146:149], v220 offset:26752
	v_add_f32_e32 v231, v231, v70
	v_add_f32_e32 v232, v232, v71
	v_add_f32_e32 v231, v231, v72
	v_add_f32_e32 v232, v232, v73
	v_cvt_pk_bf16_f32 v66, v66, v67
	v_cvt_pk_bf16_f32 v67, v68, v69
	v_mfma_f32_32x32x16_bf16 v[50:65], v[150:153], v[102:105], v[50:65]
	ds_read_b128 v[150:153], v220 offset:33408
	v_cvt_pk_bf16_f32 v68, v70, v71
	v_cvt_pk_bf16_f32 v69, v72, v73
	v_exp_f32_e32 v74, v74
	v_exp_f32_e32 v75, v75
	s_waitcnt lgkmcnt(4)
	v_mfma_f32_32x32x16_bf16 v[34:49], v[154:157], v[106:109], v[34:49]
	ds_read_b128 v[154:157], v220 offset:26784
	v_exp_f32_e32 v76, v76
	v_exp_f32_e32 v77, v77
	v_add_f32_e32 v231, v231, v74
	v_add_f32_e32 v232, v232, v75
	v_mfma_f32_32x32x16_bf16 v[50:65], v[158:161], v[106:109], v[50:65]
	ds_read_b128 v[158:161], v220 offset:33440
	v_exp_f32_e32 v78, v78
	v_exp_f32_e32 v79, v79
	v_add_f32_e32 v231, v231, v76
	v_add_f32_e32 v232, v232, v77
	v_exp_f32_e32 v80, v80
	s_waitcnt lgkmcnt(4)
	v_mfma_f32_32x32x16_bf16 v[34:49], v[138:141], v[110:113], v[34:49]
	ds_read_b64 v[162:163], v221 offset:8704
	ds_read_b64 v[164:165], v221 offset:8720
	v_exp_f32_e32 v81, v81
	v_add_f32_e32 v231, v231, v78
	v_add_f32_e32 v232, v232, v79
	v_add_f32_e32 v231, v231, v80
	v_mfma_f32_32x32x16_bf16 v[50:65], v[142:145], v[110:113], v[50:65]
	ds_read_b64 v[166:167], v221 offset:13056
	ds_read_b64 v[168:169], v221 offset:13072
	v_add_f32_e32 v232, v232, v81
	v_cvt_pk_bf16_f32 v74, v74, v75
	v_cvt_pk_bf16_f32 v75, v76, v77
	v_cvt_pk_bf16_f32 v76, v78, v79
	v_cvt_pk_bf16_f32 v77, v80, v81
	v_exp_f32_e32 v82, v82
	s_waitcnt lgkmcnt(6)
	v_mfma_f32_32x32x16_bf16 v[34:49], v[146:149], v[114:117], v[34:49]
	ds_read_b64 v[170:171], v221 offset:8736
	ds_read_b64 v[172:173], v221 offset:8752
	v_exp_f32_e32 v83, v83
	v_exp_f32_e32 v84, v84
	v_exp_f32_e32 v85, v85
	v_mfma_f32_32x32x16_bf16 v[50:65], v[150:153], v[114:117], v[50:65]
	ds_read_b64 v[174:175], v221 offset:13088
	ds_read_b64 v[176:177], v221 offset:13104
	v_add_f32_e32 v231, v231, v82
	v_add_f32_e32 v232, v232, v83
	v_exp_f32_e32 v86, v86
	v_exp_f32_e32 v87, v87
	s_waitcnt lgkmcnt(8)
	v_mfma_f32_32x32x16_bf16 v[34:49], v[154:157], v[118:121], v[34:49]
	ds_read_b64 v[180:181], v221 offset:8768
	ds_read_b64 v[182:183], v221 offset:8784
	v_add_f32_e32 v231, v231, v84
	v_add_f32_e32 v232, v232, v85
	v_exp_f32_e32 v88, v88
	v_exp_f32_e32 v89, v89
	v_mfma_f32_32x32x16_bf16 v[50:65], v[158:161], v[118:121], v[50:65]
	ds_read_b64 v[184:185], v221 offset:13120
	ds_read_b64 v[186:187], v221 offset:13136
	v_add_f32_e32 v231, v231, v86
	v_add_f32_e32 v232, v232, v87
	v_add_f32_e32 v231, v231, v88
	v_add_f32_e32 v232, v232, v89
	v_cvt_pk_bf16_f32 v82, v82, v83
	v_cvt_pk_bf16_f32 v83, v84, v85
	v_cvt_pk_bf16_f32 v84, v86, v87
	s_waitcnt lgkmcnt(8)
	v_mfma_f32_32x32x16_bf16 v[2:17], v[162:165], v[66:69], v[2:17]
	ds_read_b64 v[188:189], v221 offset:8800
	ds_read_b64 v[190:191], v221 offset:8816
	v_cvt_pk_bf16_f32 v85, v88, v89
	v_exp_f32_e32 v90, v90
	v_exp_f32_e32 v91, v91
	v_exp_f32_e32 v92, v92
	v_mfma_f32_32x32x16_bf16 v[18:33], v[166:169], v[66:69], v[18:33]
	ds_read_b64 v[192:193], v221 offset:13152
	ds_read_b64 v[194:195], v221 offset:13168
	v_exp_f32_e32 v93, v93
	v_add_f32_e32 v231, v231, v90
	v_add_f32_e32 v232, v232, v91
	v_exp_f32_e32 v94, v94
	s_waitcnt lgkmcnt(8)
	v_mfma_f32_32x32x16_bf16 v[2:17], v[170:173], v[74:77], v[2:17]
	v_exp_f32_e32 v95, v95
	v_add_f32_e32 v231, v231, v92
	v_add_f32_e32 v232, v232, v93
	v_exp_f32_e32 v96, v96
	v_mfma_f32_32x32x16_bf16 v[18:33], v[174:177], v[74:77], v[18:33]
	s_waitcnt vmcnt(0)
	ds_write_b64 v225, v[212:213] offset:26112
	ds_write_b64 v225, v[214:215] offset:26120
	v_exp_f32_e32 v97, v97
	v_add_f32_e32 v231, v231, v94
	v_add_f32_e32 v232, v232, v95
	v_add_f32_e32 v231, v231, v96
	v_add_f32_e32 v232, v232, v97
	s_waitcnt lgkmcnt(6)
	v_mfma_f32_32x32x16_bf16 v[2:17], v[180:183], v[82:85], v[2:17]
	v_cvt_pk_bf16_f32 v90, v90, v91
	v_cvt_pk_bf16_f32 v91, v92, v93
	v_cvt_pk_bf16_f32 v92, v94, v95
	v_cvt_pk_bf16_f32 v93, v96, v97
	v_max3_f32 v234, v34, v35, v36
	v_max3_f32 v235, v50, v51, v52
	v_mfma_f32_32x32x16_bf16 v[18:33], v[184:187], v[82:85], v[18:33]
	v_max3_f32 v234, v234, v37, v38
	v_max3_f32 v235, v235, v53, v54
	v_max3_f32 v234, v234, v39, v40
	v_max3_f32 v235, v235, v55, v56
	v_max3_f32 v234, v234, v41, v42
	v_max3_f32 v235, v235, v57, v58
	v_max3_f32 v234, v234, v43, v44
	s_waitcnt lgkmcnt(2)
	v_mfma_f32_32x32x16_bf16 v[2:17], v[188:191], v[90:93], v[2:17]
	v_max3_f32 v235, v235, v59, v60
	v_max3_f32 v234, v234, v45, v46
	v_max3_f32 v235, v235, v61, v62
	v_max3_f32 v234, v234, v47, v48
	v_max3_f32 v235, v235, v63, v64
	v_max3_f32 v234, v234, v49, v65
	v_mfma_f32_32x32x16_bf16 v[18:33], v[192:195], v[90:93], v[18:33]
	v_max_f32_e32 v234, v234, v235
	v_mov_b32_e32 v235, v234
	s_nop 1
	v_permlane32_swap_b32_e32 v234, v235
	v_max_f32_e32 v233, v234, v235
	v_cmp_lt_f32_e32 vcc, 4.0, v233
	s_cbranch_vccz .Lmla_nr_t1
	s_nop 15
	v_max_f32_e32 v234, 0, v233
	v_exp_f32_e64 v235, -v234
	v_add_f32_e32 v230, v230, v234
	v_sub_f32_e32 v34, v34, v234
	v_sub_f32_e32 v35, v35, v234
	v_sub_f32_e32 v36, v36, v234
	v_sub_f32_e32 v37, v37, v234
	v_sub_f32_e32 v38, v38, v234
	v_sub_f32_e32 v39, v39, v234
	v_sub_f32_e32 v40, v40, v234
	v_sub_f32_e32 v41, v41, v234
	v_sub_f32_e32 v42, v42, v234
	v_sub_f32_e32 v43, v43, v234
	v_sub_f32_e32 v44, v44, v234
	v_sub_f32_e32 v45, v45, v234
	v_sub_f32_e32 v46, v46, v234
	v_sub_f32_e32 v47, v47, v234
	v_sub_f32_e32 v48, v48, v234
	v_sub_f32_e32 v49, v49, v234
	v_sub_f32_e32 v50, v50, v234
	v_sub_f32_e32 v51, v51, v234
	v_sub_f32_e32 v52, v52, v234
	v_sub_f32_e32 v53, v53, v234
	v_sub_f32_e32 v54, v54, v234
	v_sub_f32_e32 v55, v55, v234
	v_sub_f32_e32 v56, v56, v234
	v_sub_f32_e32 v57, v57, v234
	v_sub_f32_e32 v58, v58, v234
	v_sub_f32_e32 v59, v59, v234
	v_sub_f32_e32 v60, v60, v234
	v_sub_f32_e32 v61, v61, v234
	v_sub_f32_e32 v62, v62, v234
	v_sub_f32_e32 v63, v63, v234
	v_sub_f32_e32 v64, v64, v234
	v_sub_f32_e32 v65, v65, v234
	v_mul_f32_e32 v231, v231, v235
	v_mul_f32_e32 v232, v232, v235
	v_mul_f32_e32 v2, v2, v235
	v_mul_f32_e32 v3, v3, v235
	v_mul_f32_e32 v4, v4, v235
	v_mul_f32_e32 v5, v5, v235
	v_mul_f32_e32 v6, v6, v235
	v_mul_f32_e32 v7, v7, v235
	v_mul_f32_e32 v8, v8, v235
	v_mul_f32_e32 v9, v9, v235
	v_mul_f32_e32 v10, v10, v235
	v_mul_f32_e32 v11, v11, v235
	v_mul_f32_e32 v12, v12, v235
	v_mul_f32_e32 v13, v13, v235
	v_mul_f32_e32 v14, v14, v235
	v_mul_f32_e32 v15, v15, v235
	v_mul_f32_e32 v16, v16, v235
	v_mul_f32_e32 v17, v17, v235
	v_mul_f32_e32 v18, v18, v235
	v_mul_f32_e32 v19, v19, v235
	v_mul_f32_e32 v20, v20, v235
	v_mul_f32_e32 v21, v21, v235
	v_mul_f32_e32 v22, v22, v235
	v_mul_f32_e32 v23, v23, v235
	v_mul_f32_e32 v24, v24, v235
	v_mul_f32_e32 v25, v25, v235
	v_mul_f32_e32 v26, v26, v235
	v_mul_f32_e32 v27, v27, v235
	v_mul_f32_e32 v28, v28, v235
	v_mul_f32_e32 v29, v29, v235
	v_mul_f32_e32 v30, v30, v235
	v_mul_f32_e32 v31, v31, v235
	v_mul_f32_e32 v32, v32, v235
	v_mul_f32_e32 v33, v33, v235
	v_sub_f32_e32 v122, 0, v230
	v_mov_b32_e32 v123, v122
	v_mov_b32_e32 v124, v122
	v_mov_b32_e32 v125, v122
	v_mov_b32_e32 v126, v122
	v_mov_b32_e32 v127, v122
	v_mov_b32_e32 v128, v122
	v_mov_b32_e32 v129, v122
	v_mov_b32_e32 v130, v122
	v_mov_b32_e32 v131, v122
	v_mov_b32_e32 v132, v122
	v_mov_b32_e32 v133, v122
	v_mov_b32_e32 v134, v122
	v_mov_b32_e32 v135, v122
	v_mov_b32_e32 v136, v122
	v_mov_b32_e32 v137, v122
.Lmla_nr_t1:
	ds_read_b128 v[138:141], v220 offset:39936
	ds_read_b128 v[142:145], v220 offset:46592
	ds_read_b128 v[146:149], v220 offset:39968
	ds_read_b128 v[150:153], v220 offset:46624
	ds_read_b128 v[154:157], v220 offset:40000
	ds_read_b128 v[158:161], v220 offset:46656
	s_waitcnt lgkmcnt(6)
	s_barrier
	global_load_dwordx2 v[200:201], v236, s[14:15] offset:0
	global_load_dwordx2 v[202:203], v236, s[14:15] offset:16
	global_load_dwordx2 v[204:205], v236, s[14:15] offset:32
	global_load_dwordx2 v[206:207], v236, s[14:15] offset:48
	global_load_dwordx2 v[208:209], v236, s[14:15] offset:64
	global_load_dwordx2 v[210:211], v236, s[14:15] offset:80
	global_load_dwordx2 v[212:213], v236, s[14:15] offset:96
	global_load_dwordx2 v[214:215], v236, s[14:15] offset:112
	v_exp_f32_e32 v34, v34
	v_exp_f32_e32 v35, v35
	v_exp_f32_e32 v36, v36
	v_exp_f32_e32 v37, v37
	s_waitcnt lgkmcnt(4)
	v_mfma_f32_32x32x16_bf16 v[66:81], v[138:141], v[98:101], v[122:137]
	ds_read_b128 v[138:141], v220 offset:40032
	v_add_f32_e32 v231, v231, v34
	v_add_f32_e32 v232, v232, v35
	v_exp_f32_e32 v38, v38
	v_exp_f32_e32 v39, v39
	v_mfma_f32_32x32x16_bf16 v[82:97], v[142:145], v[98:101], v[122:137]
	ds_read_b128 v[142:145], v220 offset:46688
	v_add_f32_e32 v231, v231, v36
	v_add_f32_e32 v232, v232, v37
	v_exp_f32_e32 v40, v40
	v_exp_f32_e32 v41, v41
	s_waitcnt lgkmcnt(4)
	v_mfma_f32_32x32x16_bf16 v[66:81], v[146:149], v[102:105], v[66:81]
	ds_read_b128 v[146:149], v220 offset:40064
	v_add_f32_e32 v231, v231, v38
	v_add_f32_e32 v232, v232, v39
	v_add_f32_e32 v231, v231, v40
	v_add_f32_e32 v232, v232, v41
	v_cvt_pk_bf16_f32 v34, v34, v35
	v_cvt_pk_bf16_f32 v35, v36, v37
	v_mfma_f32_32x32x16_bf16 v[82:97], v[150:153], v[102:105], v[82:97]
	ds_read_b128 v[150:153], v220 offset:46720
	v_cvt_pk_bf16_f32 v36, v38, v39
	v_cvt_pk_bf16_f32 v37, v40, v41
	v_exp_f32_e32 v42, v42
	v_exp_f32_e32 v43, v43
	s_waitcnt lgkmcnt(4)
	v_mfma_f32_32x32x16_bf16 v[66:81], v[154:157], v[106:109], v[66:81]
	ds_read_b128 v[154:157], v220 offset:40096
	v_exp_f32_e32 v44, v44
	v_exp_f32_e32 v45, v45
	v_add_f32_e32 v231, v231, v42
	v_add_f32_e32 v232, v232, v43
	v_mfma_f32_32x32x16_bf16 v[82:97], v[158:161], v[106:109], v[82:97]
	ds_read_b128 v[158:161], v220 offset:46752
	v_exp_f32_e32 v46, v46
	v_exp_f32_e32 v47, v47
	v_add_f32_e32 v231, v231, v44
	v_add_f32_e32 v232, v232, v45
	v_exp_f32_e32 v48, v48
	s_waitcnt lgkmcnt(4)
	v_mfma_f32_32x32x16_bf16 v[66:81], v[138:141], v[110:113], v[66:81]
	ds_read_b64 v[162:163], v221 offset:17408
	ds_read_b64 v[164:165], v221 offset:17424
	v_exp_f32_e32 v49, v49
	v_add_f32_e32 v231, v231, v46
	v_add_f32_e32 v232, v232, v47
	v_add_f32_e32 v231, v231, v48
	v_mfma_f32_32x32x16_bf16 v[82:97], v[142:145], v[110:113], v[82:97]
	ds_read_b64 v[166:167], v221 offset:21760
	ds_read_b64 v[168:169], v221 offset:21776
	v_add_f32_e32 v232, v232, v49
	v_cvt_pk_bf16_f32 v42, v42, v43
	v_cvt_pk_bf16_f32 v43, v44, v45
	v_cvt_pk_bf16_f32 v44, v46, v47
	v_cvt_pk_bf16_f32 v45, v48, v49
	v_exp_f32_e32 v50, v50
	s_waitcnt lgkmcnt(6)
	v_mfma_f32_32x32x16_bf16 v[66:81], v[146:149], v[114:117], v[66:81]
	ds_read_b64 v[170:171], v221 offset:17440
	ds_read_b64 v[172:173], v221 offset:17456
	v_exp_f32_e32 v51, v51
	v_exp_f32_e32 v52, v52
	v_exp_f32_e32 v53, v53
	v_mfma_f32_32x32x16_bf16 v[82:97], v[150:153], v[114:117], v[82:97]
	ds_read_b64 v[174:175], v221 offset:21792
	ds_read_b64 v[176:177], v221 offset:21808
	v_add_f32_e32 v231, v231, v50
	v_add_f32_e32 v232, v232, v51
	v_exp_f32_e32 v54, v54
	v_exp_f32_e32 v55, v55
	s_waitcnt lgkmcnt(8)
	v_mfma_f32_32x32x16_bf16 v[66:81], v[154:157], v[118:121], v[66:81]
	ds_read_b64 v[180:181], v221 offset:17472
	ds_read_b64 v[182:183], v221 offset:17488
	v_add_f32_e32 v231, v231, v52
	v_add_f32_e32 v232, v232, v53
	v_exp_f32_e32 v56, v56
	v_exp_f32_e32 v57, v57
	v_mfma_f32_32x32x16_bf16 v[82:97], v[158:161], v[118:121], v[82:97]
	ds_read_b64 v[184:185], v221 offset:21824
	ds_read_b64 v[186:187], v221 offset:21840
	v_add_f32_e32 v231, v231, v54
	v_add_f32_e32 v232, v232, v55
	v_add_f32_e32 v231, v231, v56
	v_add_f32_e32 v232, v232, v57
	v_cvt_pk_bf16_f32 v50, v50, v51
	v_cvt_pk_bf16_f32 v51, v52, v53
	v_cvt_pk_bf16_f32 v52, v54, v55
	s_waitcnt lgkmcnt(8)
	v_mfma_f32_32x32x16_bf16 v[2:17], v[162:165], v[34:37], v[2:17]
	ds_read_b64 v[188:189], v221 offset:17504
	ds_read_b64 v[190:191], v221 offset:17520
	v_cvt_pk_bf16_f32 v53, v56, v57
	v_exp_f32_e32 v58, v58
	v_exp_f32_e32 v59, v59
	v_exp_f32_e32 v60, v60
	v_mfma_f32_32x32x16_bf16 v[18:33], v[166:169], v[34:37], v[18:33]
	ds_read_b64 v[192:193], v221 offset:21856
	ds_read_b64 v[194:195], v221 offset:21872
	v_exp_f32_e32 v61, v61
	v_add_f32_e32 v231, v231, v58
	v_add_f32_e32 v232, v232, v59
	v_exp_f32_e32 v62, v62
	s_waitcnt lgkmcnt(8)
	v_mfma_f32_32x32x16_bf16 v[2:17], v[170:173], v[42:45], v[2:17]
	v_exp_f32_e32 v63, v63
	v_add_f32_e32 v231, v231, v60
	v_add_f32_e32 v232, v232, v61
	v_exp_f32_e32 v64, v64
	v_mfma_f32_32x32x16_bf16 v[18:33], v[174:177], v[42:45], v[18:33]
	v_exp_f32_e32 v65, v65
	v_add_f32_e32 v231, v231, v62
	v_add_f32_e32 v232, v232, v63
	v_add_f32_e32 v231, v231, v64
	v_add_f32_e32 v232, v232, v65
	s_waitcnt lgkmcnt(4)
	v_mfma_f32_32x32x16_bf16 v[2:17], v[180:183], v[50:53], v[2:17]
	v_cvt_pk_bf16_f32 v58, v58, v59
	v_cvt_pk_bf16_f32 v59, v60, v61
	v_cvt_pk_bf16_f32 v60, v62, v63
	v_cvt_pk_bf16_f32 v61, v64, v65
	v_max3_f32 v234, v66, v67, v68
	v_max3_f32 v235, v82, v83, v84
	v_mfma_f32_32x32x16_bf16 v[18:33], v[184:187], v[50:53], v[18:33]
	v_max3_f32 v234, v234, v69, v70
	v_max3_f32 v235, v235, v85, v86
	v_max3_f32 v234, v234, v71, v72
	v_max3_f32 v235, v235, v87, v88
	v_max3_f32 v234, v234, v73, v74
	v_max3_f32 v235, v235, v89, v90
	v_max3_f32 v234, v234, v75, v76
	s_waitcnt lgkmcnt(0)
	v_mfma_f32_32x32x16_bf16 v[2:17], v[188:191], v[58:61], v[2:17]
	v_max3_f32 v235, v235, v91, v92
	v_max3_f32 v234, v234, v77, v78
	v_max3_f32 v235, v235, v93, v94
	v_max3_f32 v234, v234, v79, v80
	v_max3_f32 v235, v235, v95, v96
	v_max3_f32 v234, v234, v81, v97
	v_mfma_f32_32x32x16_bf16 v[18:33], v[192:195], v[58:61], v[18:33]
	v_max_f32_e32 v234, v234, v235
	v_mov_b32_e32 v235, v234
	s_nop 1
	v_permlane32_swap_b32_e32 v234, v235
	v_max_f32_e32 v233, v234, v235
	v_cmp_lt_f32_e32 vcc, 4.0, v233
	s_cbranch_vccz .Lmla_nr_t2
	s_nop 15
	v_max_f32_e32 v234, 0, v233
	v_exp_f32_e64 v235, -v234
	v_add_f32_e32 v230, v230, v234
	v_sub_f32_e32 v66, v66, v234
	v_sub_f32_e32 v67, v67, v234
	v_sub_f32_e32 v68, v68, v234
	v_sub_f32_e32 v69, v69, v234
	v_sub_f32_e32 v70, v70, v234
	v_sub_f32_e32 v71, v71, v234
	v_sub_f32_e32 v72, v72, v234
	v_sub_f32_e32 v73, v73, v234
	v_sub_f32_e32 v74, v74, v234
	v_sub_f32_e32 v75, v75, v234
	v_sub_f32_e32 v76, v76, v234
	v_sub_f32_e32 v77, v77, v234
	v_sub_f32_e32 v78, v78, v234
	v_sub_f32_e32 v79, v79, v234
	v_sub_f32_e32 v80, v80, v234
	v_sub_f32_e32 v81, v81, v234
	v_sub_f32_e32 v82, v82, v234
	v_sub_f32_e32 v83, v83, v234
	v_sub_f32_e32 v84, v84, v234
	v_sub_f32_e32 v85, v85, v234
	v_sub_f32_e32 v86, v86, v234
	v_sub_f32_e32 v87, v87, v234
	v_sub_f32_e32 v88, v88, v234
	v_sub_f32_e32 v89, v89, v234
	v_sub_f32_e32 v90, v90, v234
	v_sub_f32_e32 v91, v91, v234
	v_sub_f32_e32 v92, v92, v234
	v_sub_f32_e32 v93, v93, v234
	v_sub_f32_e32 v94, v94, v234
	v_sub_f32_e32 v95, v95, v234
	v_sub_f32_e32 v96, v96, v234
	v_sub_f32_e32 v97, v97, v234
	v_mul_f32_e32 v231, v231, v235
	v_mul_f32_e32 v232, v232, v235
	v_mul_f32_e32 v2, v2, v235
	v_mul_f32_e32 v3, v3, v235
	v_mul_f32_e32 v4, v4, v235
	v_mul_f32_e32 v5, v5, v235
	v_mul_f32_e32 v6, v6, v235
	v_mul_f32_e32 v7, v7, v235
	v_mul_f32_e32 v8, v8, v235
	v_mul_f32_e32 v9, v9, v235
	v_mul_f32_e32 v10, v10, v235
	v_mul_f32_e32 v11, v11, v235
	v_mul_f32_e32 v12, v12, v235
	v_mul_f32_e32 v13, v13, v235
	v_mul_f32_e32 v14, v14, v235
	v_mul_f32_e32 v15, v15, v235
	v_mul_f32_e32 v16, v16, v235
	v_mul_f32_e32 v17, v17, v235
	v_mul_f32_e32 v18, v18, v235
	v_mul_f32_e32 v19, v19, v235
	v_mul_f32_e32 v20, v20, v235
	v_mul_f32_e32 v21, v21, v235
	v_mul_f32_e32 v22, v22, v235
	v_mul_f32_e32 v23, v23, v235
	v_mul_f32_e32 v24, v24, v235
	v_mul_f32_e32 v25, v25, v235
	v_mul_f32_e32 v26, v26, v235
	v_mul_f32_e32 v27, v27, v235
	v_mul_f32_e32 v28, v28, v235
	v_mul_f32_e32 v29, v29, v235
	v_mul_f32_e32 v30, v30, v235
	v_mul_f32_e32 v31, v31, v235
	v_mul_f32_e32 v32, v32, v235
	v_mul_f32_e32 v33, v33, v235
	v_sub_f32_e32 v122, 0, v230
	v_mov_b32_e32 v123, v122
	v_mov_b32_e32 v124, v122
	v_mov_b32_e32 v125, v122
	v_mov_b32_e32 v126, v122
	v_mov_b32_e32 v127, v122
	v_mov_b32_e32 v128, v122
	v_mov_b32_e32 v129, v122
	v_mov_b32_e32 v130, v122
	v_mov_b32_e32 v131, v122
	v_mov_b32_e32 v132, v122
	v_mov_b32_e32 v133, v122
	v_mov_b32_e32 v134, v122
	v_mov_b32_e32 v135, v122
	v_mov_b32_e32 v136, v122
	v_mov_b32_e32 v137, v122
.Lmla_nr_t2:
	s_waitcnt lgkmcnt(0)
	s_barrier
	ds_read_b64 v[162:163], v221 offset:26112
	ds_read_b64 v[164:165], v221 offset:26128
	ds_read_b64 v[166:167], v221 offset:30464
	ds_read_b64 v[168:169], v221 offset:30480
	ds_read_b64 v[170:171], v221 offset:26144
	ds_read_b64 v[172:173], v221 offset:26160
	v_exp_f32_e32 v66, v66
	v_exp_f32_e32 v67, v67
	v_exp_f32_e32 v68, v68
	v_exp_f32_e32 v69, v69
	v_add_f32_e32 v231, v231, v66
	v_add_f32_e32 v232, v232, v67
	v_exp_f32_e32 v70, v70
	v_exp_f32_e32 v71, v71
	v_add_f32_e32 v231, v231, v68
	v_add_f32_e32 v232, v232, v69
	v_exp_f32_e32 v72, v72
	v_exp_f32_e32 v73, v73
	v_add_f32_e32 v231, v231, v70
	v_add_f32_e32 v232, v232, v71
	v_add_f32_e32 v231, v231, v72
	v_add_f32_e32 v232, v232, v73
	v_cvt_pk_bf16_f32 v66, v66, v67
	v_cvt_pk_bf16_f32 v67, v68, v69
	v_cvt_pk_bf16_f32 v68, v70, v71
	v_cvt_pk_bf16_f32 v69, v72, v73
	s_waitcnt lgkmcnt(2)
	s_nop 0
	v_mfma_f32_32x32x16_bf16 v[2:17], v[162:165], v[66:69], v[2:17]
	ds_read_b64 v[174:175], v221 offset:30496
	ds_read_b64 v[176:177], v221 offset:30512
	v_mfma_f32_32x32x16_bf16 v[18:33], v[166:169], v[66:69], v[18:33]
	ds_read_b64 v[180:181], v221 offset:26176
	ds_read_b64 v[182:183], v221 offset:26192
	v_exp_f32_e32 v74, v74
	v_exp_f32_e32 v75, v75
	v_exp_f32_e32 v76, v76
	v_exp_f32_e32 v77, v77
	v_add_f32_e32 v231, v231, v74
	v_add_f32_e32 v232, v232, v75
	v_exp_f32_e32 v78, v78
	v_exp_f32_e32 v79, v79
	v_add_f32_e32 v231, v231, v76
	v_add_f32_e32 v232, v232, v77
	v_exp_f32_e32 v80, v80
	v_exp_f32_e32 v81, v81
	v_add_f32_e32 v231, v231, v78
	v_add_f32_e32 v232, v232, v79
	v_add_f32_e32 v231, v231, v80
	v_add_f32_e32 v232, v232, v81
	v_cvt_pk_bf16_f32 v74, v74, v75
	v_cvt_pk_bf16_f32 v75, v76, v77
	v_cvt_pk_bf16_f32 v76, v78, v79
	v_cvt_pk_bf16_f32 v77, v80, v81
	s_waitcnt lgkmcnt(2)
	s_nop 0
	v_mfma_f32_32x32x16_bf16 v[2:17], v[170:173], v[74:77], v[2:17]
	ds_read_b64 v[184:185], v221 offset:30528
	ds_read_b64 v[186:187], v221 offset:30544
	v_mfma_f32_32x32x16_bf16 v[18:33], v[174:177], v[74:77], v[18:33]
	ds_read_b64 v[188:189], v221 offset:26208
	ds_read_b64 v[190:191], v221 offset:26224
	v_exp_f32_e32 v82, v82
	v_exp_f32_e32 v83, v83
	v_exp_f32_e32 v84, v84
	v_exp_f32_e32 v85, v85
	v_add_f32_e32 v231, v231, v82
	v_add_f32_e32 v232, v232, v83
	v_exp_f32_e32 v86, v86
	v_exp_f32_e32 v87, v87
	v_add_f32_e32 v231, v231, v84
	v_add_f32_e32 v232, v232, v85
	v_exp_f32_e32 v88, v88
	v_exp_f32_e32 v89, v89
	v_add_f32_e32 v231, v231, v86
	v_add_f32_e32 v232, v232, v87
	v_add_f32_e32 v231, v231, v88
	v_add_f32_e32 v232, v232, v89
	v_cvt_pk_bf16_f32 v82, v82, v83
	v_cvt_pk_bf16_f32 v83, v84, v85
	v_cvt_pk_bf16_f32 v84, v86, v87
	v_cvt_pk_bf16_f32 v85, v88, v89
	s_waitcnt lgkmcnt(2)
	s_nop 0
	v_mfma_f32_32x32x16_bf16 v[2:17], v[180:183], v[82:85], v[2:17]
	ds_read_b64 v[192:193], v221 offset:30560
	ds_read_b64 v[194:195], v221 offset:30576
	v_mfma_f32_32x32x16_bf16 v[18:33], v[184:187], v[82:85], v[18:33]
	v_exp_f32_e32 v90, v90
	v_exp_f32_e32 v91, v91
	v_exp_f32_e32 v92, v92
	v_exp_f32_e32 v93, v93
	v_add_f32_e32 v231, v231, v90
	v_add_f32_e32 v232, v232, v91
	v_exp_f32_e32 v94, v94
	v_exp_f32_e32 v95, v95
	v_add_f32_e32 v231, v231, v92
	v_add_f32_e32 v232, v232, v93
	v_exp_f32_e32 v96, v96
	v_exp_f32_e32 v97, v97
	v_add_f32_e32 v231, v231, v94
	v_add_f32_e32 v232, v232, v95
	v_add_f32_e32 v231, v231, v96
	v_add_f32_e32 v232, v232, v97
	v_cvt_pk_bf16_f32 v90, v90, v91
	v_cvt_pk_bf16_f32 v91, v92, v93
	v_cvt_pk_bf16_f32 v92, v94, v95
	v_cvt_pk_bf16_f32 v93, v96, v97
	s_waitcnt lgkmcnt(0)
	s_nop 0
	v_mfma_f32_32x32x16_bf16 v[2:17], v[188:191], v[90:93], v[2:17]
	v_mfma_f32_32x32x16_bf16 v[18:33], v[192:195], v[90:93], v[18:33]
	s_waitcnt lgkmcnt(0)
	s_barrier
	v_add_f32_e32 v231, v231, v232
	v_mov_b32_e32 v235, v231
	s_nop 1
	v_permlane32_swap_b32_e32 v231, v235
	v_add_f32_e32 v234, v231, v235
	v_div_scale_f32 v235, s[22:23], v234, v234, 1.0
	v_rcp_f32_e32 v179, v235
	v_div_scale_f32 v196, vcc, 1.0, v234, 1.0
	v_fma_f32 v197, -v235, v179, 1.0
	v_fmac_f32_e32 v179, v197, v179
	v_mul_f32_e32 v197, v196, v179
	v_fma_f32 v199, -v235, v197, v196
	v_fmac_f32_e32 v197, v199, v179
	v_fma_f32 v235, -v235, v197, v196
	v_div_fmas_f32 v235, v235, v179, v197
	v_div_fixup_f32 v234, v235, v234, 1.0
	s_nop 15
	v_mul_f32_e32 v2, v2, v234
	v_mul_f32_e32 v3, v3, v234
	v_mul_f32_e32 v4, v4, v234
	v_mul_f32_e32 v5, v5, v234
	v_mul_f32_e32 v6, v6, v234
	v_mul_f32_e32 v7, v7, v234
	v_mul_f32_e32 v8, v8, v234
	v_mul_f32_e32 v9, v9, v234
	v_mul_f32_e32 v10, v10, v234
	v_mul_f32_e32 v11, v11, v234
	v_mul_f32_e32 v12, v12, v234
	v_mul_f32_e32 v13, v13, v234
	v_mul_f32_e32 v14, v14, v234
	v_mul_f32_e32 v15, v15, v234
	v_mul_f32_e32 v16, v16, v234
	v_mul_f32_e32 v17, v17, v234
	v_mul_f32_e32 v18, v18, v234
	v_mul_f32_e32 v19, v19, v234
	v_mul_f32_e32 v20, v20, v234
	v_mul_f32_e32 v21, v21, v234
	v_mul_f32_e32 v22, v22, v234
	v_mul_f32_e32 v23, v23, v234
	v_mul_f32_e32 v24, v24, v234
	v_mul_f32_e32 v25, v25, v234
	v_mul_f32_e32 v26, v26, v234
	v_mul_f32_e32 v27, v27, v234
	v_mul_f32_e32 v28, v28, v234
	v_mul_f32_e32 v29, v29, v234
	v_mul_f32_e32 v30, v30, v234
	v_mul_f32_e32 v31, v31, v234
	v_mul_f32_e32 v32, v32, v234
	v_mul_f32_e32 v33, v33, v234
	s_waitcnt vmcnt(0)
	v_lshlrev_b32_e32 v179, 16, v200
	v_and_b32_e32 v196, 0xffff0000, v200
	v_lshlrev_b32_e32 v197, 16, v201
	v_and_b32_e32 v199, 0xffff0000, v201
	v_mul_f32_e32 v2, v2, v179
	v_mul_f32_e32 v3, v3, v196
	v_mul_f32_e32 v4, v4, v197
	v_mul_f32_e32 v5, v5, v199
	v_cvt_pk_bf16_f32 v200, v2, v3
	v_cvt_pk_bf16_f32 v201, v4, v5
	global_store_dwordx2 v236, v[200:201], s[14:15] offset:0
	v_lshlrev_b32_e32 v179, 16, v202
	v_and_b32_e32 v196, 0xffff0000, v202
	v_lshlrev_b32_e32 v197, 16, v203
	v_and_b32_e32 v199, 0xffff0000, v203
	v_mul_f32_e32 v6, v6, v179
	v_mul_f32_e32 v7, v7, v196
	v_mul_f32_e32 v8, v8, v197
	v_mul_f32_e32 v9, v9, v199
	v_cvt_pk_bf16_f32 v202, v6, v7
	v_cvt_pk_bf16_f32 v203, v8, v9
	global_store_dwordx2 v236, v[202:203], s[14:15] offset:16
	v_lshlrev_b32_e32 v179, 16, v204
	v_and_b32_e32 v196, 0xffff0000, v204
	v_lshlrev_b32_e32 v197, 16, v205
	v_and_b32_e32 v199, 0xffff0000, v205
	v_mul_f32_e32 v10, v10, v179
	v_mul_f32_e32 v11, v11, v196
	v_mul_f32_e32 v12, v12, v197
	v_mul_f32_e32 v13, v13, v199
	v_cvt_pk_bf16_f32 v204, v10, v11
	v_cvt_pk_bf16_f32 v205, v12, v13
	global_store_dwordx2 v236, v[204:205], s[14:15] offset:32
	v_lshlrev_b32_e32 v179, 16, v206
	v_and_b32_e32 v196, 0xffff0000, v206
	v_lshlrev_b32_e32 v197, 16, v207
	v_and_b32_e32 v199, 0xffff0000, v207
	v_mul_f32_e32 v14, v14, v179
	v_mul_f32_e32 v15, v15, v196
	v_mul_f32_e32 v16, v16, v197
	v_mul_f32_e32 v17, v17, v199
	v_cvt_pk_bf16_f32 v206, v14, v15
	v_cvt_pk_bf16_f32 v207, v16, v17
	global_store_dwordx2 v236, v[206:207], s[14:15] offset:48
	v_lshlrev_b32_e32 v179, 16, v208
	v_and_b32_e32 v196, 0xffff0000, v208
	v_lshlrev_b32_e32 v197, 16, v209
	v_and_b32_e32 v199, 0xffff0000, v209
	v_mul_f32_e32 v18, v18, v179
	v_mul_f32_e32 v19, v19, v196
	v_mul_f32_e32 v20, v20, v197
	v_mul_f32_e32 v21, v21, v199
	v_cvt_pk_bf16_f32 v208, v18, v19
	v_cvt_pk_bf16_f32 v209, v20, v21
	global_store_dwordx2 v236, v[208:209], s[14:15] offset:64
	v_lshlrev_b32_e32 v179, 16, v210
	v_and_b32_e32 v196, 0xffff0000, v210
	v_lshlrev_b32_e32 v197, 16, v211
	v_and_b32_e32 v199, 0xffff0000, v211
	v_mul_f32_e32 v22, v22, v179
	v_mul_f32_e32 v23, v23, v196
	v_mul_f32_e32 v24, v24, v197
	v_mul_f32_e32 v25, v25, v199
	v_cvt_pk_bf16_f32 v210, v22, v23
	v_cvt_pk_bf16_f32 v211, v24, v25
	global_store_dwordx2 v236, v[210:211], s[14:15] offset:80
	v_lshlrev_b32_e32 v179, 16, v212
	v_and_b32_e32 v196, 0xffff0000, v212
	v_lshlrev_b32_e32 v197, 16, v213
	v_and_b32_e32 v199, 0xffff0000, v213
	v_mul_f32_e32 v26, v26, v179
	v_mul_f32_e32 v27, v27, v196
	v_mul_f32_e32 v28, v28, v197
	v_mul_f32_e32 v29, v29, v199
	v_cvt_pk_bf16_f32 v212, v26, v27
	v_cvt_pk_bf16_f32 v213, v28, v29
	global_store_dwordx2 v236, v[212:213], s[14:15] offset:96
	v_lshlrev_b32_e32 v179, 16, v214
	v_and_b32_e32 v196, 0xffff0000, v214
	v_lshlrev_b32_e32 v197, 16, v215
	v_and_b32_e32 v199, 0xffff0000, v215
	v_mul_f32_e32 v30, v30, v179
	v_mul_f32_e32 v31, v31, v196
	v_mul_f32_e32 v32, v32, v197
	v_mul_f32_e32 v33, v33, v199
	v_cvt_pk_bf16_f32 v214, v30, v31
	v_cvt_pk_bf16_f32 v215, v32, v33
	global_store_dwordx2 v236, v[214:215], s[14:15] offset:112
	s_add_i32 s2, s2, s88
	s_cmpk_lt_i32 s2, 0x200
	s_cbranch_scc1 .Lmla_unit
